# route: per-row top-16 of 64 score keys done in registers with a sorting network (odd-even merge sort + bitonic top-half merges) instead of 16 rounds of LDS rescans
# speedup vs baseline: 1.0076x; 1.0076x over previous
.LBB0_622:
	s_lshl_b32 s8, s2, 15
	s_or_b32 s8, s8, s47
	s_add_u32 s8, s66, s8
	s_addc_u32 s9, s67, 0
	s_lshl_b32 s2, s2, 8
	s_or_b32 s2, s2, s48
	v_lshl_add_u64 v[0:1], v[94:95], 0, s[2:3]
	v_lshl_add_u64 v[28:29], s[8:9], 0, v[92:93]
	v_mov_b32_e32 v113, v93
	v_lshl_add_u64 v[32:33], v[0:1], 0, v[120:121]
	v_lshl_add_u64 v[34:35], v[0:1], 0, v[122:123]
	v_lshl_add_u64 v[36:37], v[0:1], 0, v[124:125]
	v_lshl_add_u64 v[38:39], v[0:1], 0, v[126:127]
	v_lshl_add_u64 v[0:1], v[28:29], 0, v[112:113]
	v_mov_b32_e32 v115, v93
	v_mov_b32_e32 v117, v93
	v_mov_b32_e32 v119, v93
	global_load_dwordx4 v[0:3], v[0:1], off
	s_nop 0
	global_load_dwordx4 v[4:7], v[32:33], off
	global_load_dwordx4 v[8:11], v[34:35], off
	global_load_dwordx4 v[12:15], v[36:37], off
	global_load_dwordx4 v[16:19], v[38:39], off
	v_lshl_add_u64 v[20:21], v[28:29], 0, v[114:115]
	v_lshl_add_u64 v[24:25], v[28:29], 0, v[116:117]
	v_lshl_add_u64 v[28:29], v[28:29], 0, v[118:119]
	global_load_dwordx4 v[28:31], v[28:29], off
	s_nop 0
	global_load_dwordx4 v[20:23], v[20:21], off
	s_nop 0
	global_load_dwordx4 v[24:27], v[24:25], off
	s_barrier
	s_waitcnt vmcnt(6)
	ds_write_b128 v128, v[4:7]
	s_waitcnt vmcnt(2)
	ds_write_b128 v128, v[28:31] offset:18432
	ds_write_b128 v128, v[8:11] offset:4608
	s_waitcnt vmcnt(0)
	ds_write_b128 v128, v[24:27] offset:23040
	ds_write_b128 v128, v[12:15] offset:9216
	ds_write_b128 v128, v[20:23] offset:27648
	ds_write_b128 v128, v[16:19] offset:13824
	ds_write_b128 v128, v[0:3] offset:32256
	v_lshl_add_u64 v[0:1], s[8:9], 0, v[112:113]
	v_lshl_add_u64 v[0:1], v[0:1], 0, v[92:93]
	s_waitcnt lgkmcnt(0)
	s_barrier
	global_load_dwordx4 v[64:67], v[0:1], off offset:128
	global_load_dwordx4 v[80:83], v[32:33], off offset:128
	global_load_dwordx4 v[76:79], v[34:35], off offset:128
	global_load_dwordx4 v[72:75], v[36:37], off offset:128
	global_load_dwordx4 v[68:71], v[38:39], off offset:128
	v_lshl_add_u64 v[0:1], s[8:9], 0, v[114:115]
	v_lshl_add_u64 v[0:1], v[0:1], 0, v[92:93]
	global_load_dwordx4 v[84:87], v[0:1], off offset:128
	v_lshl_add_u64 v[0:1], s[8:9], 0, v[116:117]
	v_lshl_add_u64 v[0:1], v[0:1], 0, v[92:93]
	global_load_dwordx4 v[88:91], v[0:1], off offset:128
	v_lshl_add_u64 v[0:1], s[8:9], 0, v[118:119]
	v_lshl_add_u64 v[0:1], v[0:1], 0, v[92:93]
	global_load_dwordx4 v[180:183], v[0:1], off offset:128
	ds_read_b128 v[0:3], v130 offset:18432
	ds_read_b128 v[4:7], v129
	ds_read_b128 v[8:11], v130 offset:23040
	s_waitcnt lgkmcnt(1)
	v_mfma_f32_32x32x16_bf16 v[48:63], v[0:3], v[4:7], 0
	s_waitcnt lgkmcnt(0)
	v_mfma_f32_32x32x16_bf16 v[32:47], v[8:11], v[4:7], 0
	ds_read_b128 v[4:7], v129 offset:4608
	ds_read_b128 v[184:187], v130 offset:18464
	ds_read_b128 v[188:191], v129 offset:32
	ds_read_b128 v[192:195], v130 offset:23072
	s_waitcnt lgkmcnt(3)
	v_mfma_f32_32x32x16_bf16 v[16:31], v[0:3], v[4:7], 0
	v_mfma_f32_32x32x16_bf16 v[0:15], v[8:11], v[4:7], 0
	s_waitcnt lgkmcnt(1)
	v_mfma_f32_32x32x16_bf16 v[48:63], v[184:187], v[188:191], v[48:63]
	s_waitcnt lgkmcnt(0)
	v_mfma_f32_32x32x16_bf16 v[32:47], v[192:195], v[188:191], v[32:47]
	ds_read_b128 v[188:191], v129 offset:4640
	s_waitcnt lgkmcnt(0)
	v_mfma_f32_32x32x16_bf16 v[16:31], v[184:187], v[188:191], v[16:31]
	v_mfma_f32_32x32x16_bf16 v[0:15], v[192:195], v[188:191], v[0:15]
	ds_read_b128 v[184:187], v130 offset:18496
	ds_read_b128 v[188:191], v129 offset:64
	ds_read_b128 v[192:195], v130 offset:23104
	s_waitcnt lgkmcnt(1)
	v_mfma_f32_32x32x16_bf16 v[48:63], v[184:187], v[188:191], v[48:63]
	s_waitcnt lgkmcnt(0)
	v_mfma_f32_32x32x16_bf16 v[32:47], v[192:195], v[188:191], v[32:47]
	ds_read_b128 v[188:191], v129 offset:4672
	s_waitcnt lgkmcnt(0)
	v_mfma_f32_32x32x16_bf16 v[16:31], v[184:187], v[188:191], v[16:31]
	v_mfma_f32_32x32x16_bf16 v[0:15], v[192:195], v[188:191], v[0:15]
	ds_read_b128 v[184:187], v130 offset:18528
	ds_read_b128 v[188:191], v129 offset:96
	ds_read_b128 v[192:195], v130 offset:23136
	s_waitcnt lgkmcnt(1)
	v_mfma_f32_32x32x16_bf16 v[48:63], v[184:187], v[188:191], v[48:63]
	s_waitcnt lgkmcnt(0)
	v_mfma_f32_32x32x16_bf16 v[32:47], v[192:195], v[188:191], v[32:47]
	ds_read_b128 v[188:191], v129 offset:4704
	s_waitcnt lgkmcnt(0)
	s_barrier
	s_waitcnt vmcnt(6)
	ds_write_b128 v128, v[80:83]
	s_waitcnt vmcnt(0)
	ds_write_b128 v128, v[180:183] offset:18432
	ds_write_b128 v128, v[76:79] offset:4608
	ds_write_b128 v128, v[88:91] offset:23040
	ds_write_b128 v128, v[72:75] offset:9216
	ds_write_b128 v128, v[84:87] offset:27648
	ds_write_b128 v128, v[68:71] offset:13824
	ds_write_b128 v128, v[64:67] offset:32256
	s_waitcnt lgkmcnt(0)
	v_mfma_f32_32x32x16_bf16 v[16:31], v[184:187], v[188:191], v[16:31]
	s_barrier
	v_mfma_f32_32x32x16_bf16 v[0:15], v[192:195], v[188:191], v[0:15]
	ds_read_b128 v[64:67], v130 offset:18432
	ds_read_b128 v[68:71], v129
	ds_read_b128 v[72:75], v129 offset:32
	ds_read_b128 v[76:79], v130 offset:18464
	ds_read_b128 v[80:83], v130 offset:23040
	ds_read_b128 v[84:87], v130 offset:23072
	s_waitcnt lgkmcnt(4)
	v_mfma_f32_32x32x16_bf16 v[48:63], v[64:67], v[68:71], v[48:63]
	s_waitcnt lgkmcnt(2)
	v_mfma_f32_32x32x16_bf16 v[48:63], v[76:79], v[72:75], v[48:63]
	s_waitcnt lgkmcnt(1)
	v_mfma_f32_32x32x16_bf16 v[32:47], v[80:83], v[68:71], v[32:47]
	ds_read_b128 v[68:71], v130 offset:18496
	ds_read_b128 v[88:91], v129 offset:64
	ds_read_b128 v[180:183], v129 offset:4608
	ds_read_b128 v[184:187], v129 offset:4640
	ds_read_b128 v[188:191], v129 offset:96
	ds_read_b128 v[192:195], v130 offset:18528
	ds_read_b128 v[196:199], v129 offset:4672
	ds_read_b128 v[200:203], v129 offset:4704
	ds_read_b128 v[210:213], v130 offset:23104
	ds_read_b128 v[214:217], v130 offset:23136
	s_waitcnt lgkmcnt(0)
	s_barrier
	v_mfma_f32_32x32x16_bf16 v[48:63], v[68:71], v[88:91], v[48:63]
	v_mfma_f32_32x32x16_bf16 v[48:63], v[192:195], v[188:191], v[48:63]
	v_mfma_f32_32x32x16_bf16 v[16:31], v[64:67], v[180:183], v[16:31]
	s_nop 10
	v_not_b32_e32 v113, v48
	v_or_b32_e32 v115, 0x80000000, v48
	v_and_b32_e32 v219, 0x7fffffff, v50
	v_and_b32_e32 v218, 0x7fffffff, v49
	v_cmp_gt_i32_e32 vcc, 0, v48
	v_xor_b32_e32 v117, -1, v50
	v_pk_add_f32 v[218:219], v[218:219], 0 neg_lo:[1,1] neg_hi:[1,1]
	v_cndmask_b32_e32 v48, v115, v113, vcc
	v_cmp_gt_i32_e32 vcc, 0, v50
	v_xor_b32_e32 v119, -1, v49
	v_not_b32_e32 v64, v51
	v_cndmask_b32_e32 v50, v219, v117, vcc
	v_cmp_gt_i32_e32 vcc, 0, v49
	v_or_b32_e32 v65, 0x80000000, v51
	v_and_b32_e32 v50, 0xffffff80, v50
	v_cndmask_b32_e32 v49, v218, v119, vcc
	v_cmp_gt_i32_e32 vcc, 0, v51
	v_and_b32_e32 v49, 0xffffff80, v49
	v_and_b32_e32 v48, 0xffffff80, v48
	v_cndmask_b32_e32 v51, v65, v64, vcc
	v_and_b32_e32 v51, 0xffffff80, v51
	v_sub_u32_e32 v49, v49, v96
	v_sub_u32_e32 v50, v50, v97
	v_sub_u32_e32 v51, v51, v96
	v_bitop3_b32 v48, v48, s19, v96 bitop3:0x36
	v_add_u32_e32 v50, 0x7d, v50
	v_add_u32_e32 v49, 0x7e, v49
	v_add_u32_e32 v51, 0x7c, v51
	ds_write_b128 v136, v[48:51]
	v_not_b32_e32 v48, v52
	v_or_b32_e32 v49, 0x80000000, v52
	v_cmp_gt_i32_e32 vcc, 0, v52
	v_and_b32_e32 v51, 0x7fffffff, v54
	v_and_b32_e32 v50, 0x7fffffff, v53
	v_cndmask_b32_e32 v48, v49, v48, vcc
	v_xor_b32_e32 v49, -1, v54
	v_pk_add_f32 v[50:51], v[50:51], 0 neg_lo:[1,1] neg_hi:[1,1]
	v_cmp_gt_i32_e32 vcc, 0, v54
	v_xor_b32_e32 v52, -1, v53
	v_and_b32_e32 v48, 0xffffff80, v48
	v_cndmask_b32_e32 v49, v51, v49, vcc
	v_cmp_gt_i32_e32 vcc, 0, v53
	v_and_b32_e32 v49, 0xffffff80, v49
	v_sub_u32_e32 v49, v49, v99
	v_cndmask_b32_e32 v50, v50, v52, vcc
	v_and_b32_e32 v50, 0xffffff80, v50
	v_sub_u32_e32 v51, v50, v98
	v_add_u32_e32 v50, 0x7d, v49
	v_add_u32_e32 v49, 0x7e, v51
	v_not_b32_e32 v51, v55
	v_or_b32_e32 v52, 0x80000000, v55
	v_cmp_gt_i32_e32 vcc, 0, v55
	v_mfma_f32_32x32x16_bf16 v[32:47], v[84:87], v[72:75], v[32:47]
	v_bitop3_b32 v48, v48, s21, v96 bitop3:0x36
	v_cndmask_b32_e32 v51, v52, v51, vcc
	v_and_b32_e32 v51, 0xffffff80, v51
	v_sub_u32_e32 v51, v51, v98
	v_add_u32_e32 v51, 0x7c, v51
	ds_write_b128 v137, v[48:51]
	v_not_b32_e32 v48, v56
	v_or_b32_e32 v49, 0x80000000, v56
	v_cmp_gt_i32_e32 vcc, 0, v56
	v_and_b32_e32 v51, 0x7fffffff, v58
	v_and_b32_e32 v50, 0x7fffffff, v57
	v_cndmask_b32_e32 v48, v49, v48, vcc
	v_xor_b32_e32 v49, -1, v58
	v_pk_add_f32 v[50:51], v[50:51], 0 neg_lo:[1,1] neg_hi:[1,1]
	v_cmp_gt_i32_e32 vcc, 0, v58
	v_xor_b32_e32 v52, -1, v57
	v_mfma_f32_32x32x16_bf16 v[32:47], v[210:213], v[88:91], v[32:47]
	v_cndmask_b32_e32 v49, v51, v49, vcc
	v_cmp_gt_i32_e32 vcc, 0, v57
	v_and_b32_e32 v49, 0xffffff80, v49
	v_sub_u32_e32 v49, v49, v101
	v_cndmask_b32_e32 v50, v50, v52, vcc
	v_and_b32_e32 v50, 0xffffff80, v50
	v_sub_u32_e32 v51, v50, v100
	v_add_u32_e32 v50, 0x7d, v49
	v_add_u32_e32 v49, 0x7e, v51
	v_not_b32_e32 v51, v59
	v_or_b32_e32 v52, 0x80000000, v59
	v_cmp_gt_i32_e32 vcc, 0, v59
	v_and_b32_e32 v48, 0xffffff80, v48
	v_bitop3_b32 v48, v48, s22, v96 bitop3:0x36
	v_cndmask_b32_e32 v51, v52, v51, vcc
	v_and_b32_e32 v51, 0xffffff80, v51
	v_sub_u32_e32 v51, v51, v100
	v_add_u32_e32 v51, 0x7c, v51
	ds_write_b128 v138, v[48:51]
	v_not_b32_e32 v48, v60
	v_or_b32_e32 v49, 0x80000000, v60
	v_cmp_gt_i32_e32 vcc, 0, v60
	v_and_b32_e32 v51, 0x7fffffff, v62
	v_and_b32_e32 v50, 0x7fffffff, v61
	v_cndmask_b32_e32 v48, v49, v48, vcc
	v_xor_b32_e32 v49, -1, v62
	v_pk_add_f32 v[50:51], v[50:51], 0 neg_lo:[1,1] neg_hi:[1,1]
	v_cmp_gt_i32_e32 vcc, 0, v62
	v_xor_b32_e32 v52, -1, v61
	v_mfma_f32_32x32x16_bf16 v[32:47], v[214:217], v[188:191], v[32:47]
	v_cndmask_b32_e32 v49, v51, v49, vcc
	v_cmp_gt_i32_e32 vcc, 0, v61
	v_and_b32_e32 v49, 0xffffff80, v49
	v_sub_u32_e32 v49, v49, v103
	v_cndmask_b32_e32 v50, v50, v52, vcc
	v_and_b32_e32 v50, 0xffffff80, v50
	v_sub_u32_e32 v51, v50, v102
	v_add_u32_e32 v50, 0x7d, v49
	v_add_u32_e32 v49, 0x7e, v51
	v_not_b32_e32 v51, v63
	v_or_b32_e32 v52, 0x80000000, v63
	v_cmp_gt_i32_e32 vcc, 0, v63
	v_and_b32_e32 v48, 0xffffff80, v48
	v_bitop3_b32 v48, v48, s23, v96 bitop3:0x36
	v_cndmask_b32_e32 v51, v52, v51, vcc
	v_and_b32_e32 v51, 0xffffff80, v51
	v_sub_u32_e32 v51, v51, v102
	v_add_u32_e32 v51, 0x7c, v51
	ds_write_b128 v139, v[48:51]
	v_not_b32_e32 v48, v32
	v_or_b32_e32 v49, 0x80000000, v32
	v_cmp_gt_i32_e32 vcc, 0, v32
	v_xor_b32_e32 v50, -1, v34
	v_xor_b32_e32 v51, -1, v33
	v_cndmask_b32_e32 v32, v49, v48, vcc
	v_and_b32_e32 v49, 0x7fffffff, v34
	v_and_b32_e32 v48, 0x7fffffff, v33
	v_pk_add_f32 v[48:49], v[48:49], 0 neg_lo:[1,1] neg_hi:[1,1]
	v_cmp_gt_i32_e32 vcc, 0, v34
	v_and_b32_e32 v32, 0xffffff80, v32
	v_bitop3_b32 v32, v32, s16, v96 bitop3:0x36
	v_cndmask_b32_e32 v34, v49, v50, vcc
	v_cmp_gt_i32_e32 vcc, 0, v33
	v_or_b32_e32 v49, 0x80000000, v35
	v_and_b32_e32 v34, 0xffffff80, v34
	v_cndmask_b32_e32 v33, v48, v51, vcc
	v_not_b32_e32 v48, v35
	v_cmp_gt_i32_e32 vcc, 0, v35
	v_and_b32_e32 v33, 0xffffff80, v33
	v_sub_u32_e32 v33, v33, v104
	v_cndmask_b32_e32 v35, v49, v48, vcc
	v_and_b32_e32 v35, 0xffffff80, v35
	v_sub_u32_e32 v34, v34, v105
	v_sub_u32_e32 v35, v35, v104
	v_add_u32_e32 v34, 0x7d, v34
	v_add_u32_e32 v33, 0x7e, v33
	v_add_u32_e32 v35, 0x7c, v35
	ds_write_b128 v140, v[32:35]
	v_not_b32_e32 v32, v36
	v_or_b32_e32 v33, 0x80000000, v36
	v_cmp_gt_i32_e32 vcc, 0, v36
	v_and_b32_e32 v35, 0x7fffffff, v38
	v_and_b32_e32 v34, 0x7fffffff, v37
	v_cndmask_b32_e32 v32, v33, v32, vcc
	v_xor_b32_e32 v33, -1, v38
	v_pk_add_f32 v[34:35], v[34:35], 0 neg_lo:[1,1] neg_hi:[1,1]
	v_cmp_gt_i32_e32 vcc, 0, v38
	v_xor_b32_e32 v36, -1, v37
	v_mfma_f32_32x32x16_bf16 v[16:31], v[76:79], v[184:187], v[16:31]
	v_cndmask_b32_e32 v33, v35, v33, vcc
	v_cmp_gt_i32_e32 vcc, 0, v37
	v_and_b32_e32 v33, 0xffffff80, v33
	v_sub_u32_e32 v33, v33, v107
	v_cndmask_b32_e32 v34, v34, v36, vcc
	v_and_b32_e32 v34, 0xffffff80, v34
	v_sub_u32_e32 v35, v34, v106
	v_add_u32_e32 v34, 0x7d, v33
	v_add_u32_e32 v33, 0x7e, v35
	v_not_b32_e32 v35, v39
	v_or_b32_e32 v36, 0x80000000, v39
	v_cmp_gt_i32_e32 vcc, 0, v39
	v_and_b32_e32 v32, 0xffffff80, v32
	v_bitop3_b32 v32, v32, s24, v96 bitop3:0x36
	v_cndmask_b32_e32 v35, v36, v35, vcc
	v_and_b32_e32 v35, 0xffffff80, v35
	v_sub_u32_e32 v35, v35, v106
	v_add_u32_e32 v35, 0x7c, v35
	ds_write_b128 v141, v[32:35]
	v_not_b32_e32 v32, v40
	v_or_b32_e32 v33, 0x80000000, v40
	v_cmp_gt_i32_e32 vcc, 0, v40
	v_and_b32_e32 v35, 0x7fffffff, v42
	v_and_b32_e32 v34, 0x7fffffff, v41
	v_cndmask_b32_e32 v32, v33, v32, vcc
	v_xor_b32_e32 v33, -1, v42
	v_pk_add_f32 v[34:35], v[34:35], 0 neg_lo:[1,1] neg_hi:[1,1]
	v_cmp_gt_i32_e32 vcc, 0, v42
	v_xor_b32_e32 v36, -1, v41
	v_mfma_f32_32x32x16_bf16 v[16:31], v[68:71], v[196:199], v[16:31]
	v_cndmask_b32_e32 v33, v35, v33, vcc
	v_cmp_gt_i32_e32 vcc, 0, v41
	v_and_b32_e32 v33, 0xffffff80, v33
	v_sub_u32_e32 v33, v33, v109
	v_cndmask_b32_e32 v34, v34, v36, vcc
	v_and_b32_e32 v34, 0xffffff80, v34
	v_sub_u32_e32 v35, v34, v108
	v_add_u32_e32 v34, 0x7d, v33
	v_add_u32_e32 v33, 0x7e, v35
	v_not_b32_e32 v35, v43
	v_or_b32_e32 v36, 0x80000000, v43
	v_cmp_gt_i32_e32 vcc, 0, v43
	v_and_b32_e32 v32, 0xffffff80, v32
	v_bitop3_b32 v32, v32, s25, v96 bitop3:0x36
	v_cndmask_b32_e32 v35, v36, v35, vcc
	v_and_b32_e32 v35, 0xffffff80, v35
	v_sub_u32_e32 v35, v35, v108
	v_add_u32_e32 v35, 0x7c, v35
	ds_write_b128 v142, v[32:35]
	v_not_b32_e32 v32, v44
	v_or_b32_e32 v33, 0x80000000, v44
	v_cmp_gt_i32_e32 vcc, 0, v44
	v_and_b32_e32 v35, 0x7fffffff, v46
	v_and_b32_e32 v34, 0x7fffffff, v45
	v_cndmask_b32_e32 v32, v33, v32, vcc
	v_xor_b32_e32 v33, -1, v46
	v_pk_add_f32 v[34:35], v[34:35], 0 neg_lo:[1,1] neg_hi:[1,1]
	v_cmp_gt_i32_e32 vcc, 0, v46
	v_xor_b32_e32 v36, -1, v45
	v_mfma_f32_32x32x16_bf16 v[16:31], v[192:195], v[200:203], v[16:31]
	v_cndmask_b32_e32 v33, v35, v33, vcc
	v_cmp_gt_i32_e32 vcc, 0, v45
	v_and_b32_e32 v33, 0xffffff80, v33
	v_sub_u32_e32 v33, v33, v111
	v_cndmask_b32_e32 v34, v34, v36, vcc
	v_and_b32_e32 v34, 0xffffff80, v34
	v_sub_u32_e32 v35, v34, v110
	v_add_u32_e32 v34, 0x7d, v33
	v_add_u32_e32 v33, 0x7e, v35
	v_not_b32_e32 v35, v47
	v_or_b32_e32 v36, 0x80000000, v47
	v_cmp_gt_i32_e32 vcc, 0, v47
	v_and_b32_e32 v32, 0xffffff80, v32
	v_bitop3_b32 v32, v32, s26, v96 bitop3:0x36
	v_cndmask_b32_e32 v35, v36, v35, vcc
	v_and_b32_e32 v35, 0xffffff80, v35
	v_sub_u32_e32 v35, v35, v110
	v_add_u32_e32 v35, 0x7c, v35
	ds_write_b128 v143, v[32:35]
	v_not_b32_e32 v32, v16
	v_or_b32_e32 v33, 0x80000000, v16
	v_cmp_gt_i32_e32 vcc, 0, v16
	v_xor_b32_e32 v34, -1, v18
	v_xor_b32_e32 v35, -1, v17
	v_cndmask_b32_e32 v16, v33, v32, vcc
	v_and_b32_e32 v33, 0x7fffffff, v18
	v_and_b32_e32 v32, 0x7fffffff, v17
	v_pk_add_f32 v[32:33], v[32:33], 0 neg_lo:[1,1] neg_hi:[1,1]
	v_cmp_gt_i32_e32 vcc, 0, v18
	v_and_b32_e32 v16, 0xffffff80, v16
	v_bitop3_b32 v16, v16, s19, v96 bitop3:0x36
	v_cndmask_b32_e32 v18, v33, v34, vcc
	v_cmp_gt_i32_e32 vcc, 0, v17
	v_or_b32_e32 v33, 0x80000000, v19
	v_and_b32_e32 v18, 0xffffff80, v18
	v_cndmask_b32_e32 v17, v32, v35, vcc
	v_not_b32_e32 v32, v19
	v_cmp_gt_i32_e32 vcc, 0, v19
	v_and_b32_e32 v17, 0xffffff80, v17
	v_sub_u32_e32 v17, v17, v96
	v_cndmask_b32_e32 v19, v33, v32, vcc
	v_and_b32_e32 v19, 0xffffff80, v19
	v_sub_u32_e32 v18, v18, v97
	v_sub_u32_e32 v19, v19, v96
	v_add_u32_e32 v18, 0x7d, v18
	v_add_u32_e32 v17, 0x7e, v17
	v_add_u32_e32 v19, 0x7c, v19
	ds_write_b128 v136, v[16:19] offset:16384
	v_not_b32_e32 v16, v20
	v_or_b32_e32 v17, 0x80000000, v20
	v_cmp_gt_i32_e32 vcc, 0, v20
	v_and_b32_e32 v19, 0x7fffffff, v22
	v_and_b32_e32 v18, 0x7fffffff, v21
	v_mfma_f32_32x32x16_bf16 v[0:15], v[80:83], v[180:183], v[0:15]
	v_cndmask_b32_e32 v16, v17, v16, vcc
	v_xor_b32_e32 v17, -1, v22
	v_add_f32_e64 v18, -v18, neg(0)
	v_add_f32_e64 v19, -v19, neg(0)
	v_cmp_gt_i32_e32 vcc, 0, v22
	v_xor_b32_e32 v20, -1, v21
	v_and_b32_e32 v16, 0xffffff80, v16
	v_cndmask_b32_e32 v17, v19, v17, vcc
	v_cmp_gt_i32_e32 vcc, 0, v21
	v_and_b32_e32 v17, 0xffffff80, v17
	v_sub_u32_e32 v17, v17, v99
	v_cndmask_b32_e32 v18, v18, v20, vcc
	v_and_b32_e32 v18, 0xffffff80, v18
	v_sub_u32_e32 v19, v18, v98
	v_add_u32_e32 v18, 0x7d, v17
	v_add_u32_e32 v17, 0x7e, v19
	v_not_b32_e32 v19, v23
	v_or_b32_e32 v20, 0x80000000, v23
	v_cmp_gt_i32_e32 vcc, 0, v23
	v_mfma_f32_32x32x16_bf16 v[0:15], v[84:87], v[184:187], v[0:15]
	v_bitop3_b32 v16, v16, s21, v96 bitop3:0x36
	v_cndmask_b32_e32 v19, v20, v19, vcc
	v_and_b32_e32 v19, 0xffffff80, v19
	v_sub_u32_e32 v19, v19, v98
	v_add_u32_e32 v19, 0x7c, v19
	ds_write_b128 v137, v[16:19] offset:16384
	v_not_b32_e32 v16, v24
	v_or_b32_e32 v17, 0x80000000, v24
	v_cmp_gt_i32_e32 vcc, 0, v24
	v_and_b32_e32 v19, 0x7fffffff, v26
	v_and_b32_e32 v18, 0x7fffffff, v25
	v_cndmask_b32_e32 v16, v17, v16, vcc
	v_xor_b32_e32 v17, -1, v26
	v_pk_add_f32 v[18:19], v[18:19], 0 neg_lo:[1,1] neg_hi:[1,1]
	v_cmp_gt_i32_e32 vcc, 0, v26
	v_xor_b32_e32 v20, -1, v25
	v_mfma_f32_32x32x16_bf16 v[0:15], v[210:213], v[196:199], v[0:15]
	v_cndmask_b32_e32 v17, v19, v17, vcc
	v_cmp_gt_i32_e32 vcc, 0, v25
	v_and_b32_e32 v17, 0xffffff80, v17
	v_sub_u32_e32 v17, v17, v101
	v_cndmask_b32_e32 v18, v18, v20, vcc
	v_and_b32_e32 v18, 0xffffff80, v18
	v_sub_u32_e32 v19, v18, v100
	v_add_u32_e32 v18, 0x7d, v17
	v_add_u32_e32 v17, 0x7e, v19
	v_not_b32_e32 v19, v27
	v_or_b32_e32 v20, 0x80000000, v27
	v_cmp_gt_i32_e32 vcc, 0, v27
	v_and_b32_e32 v16, 0xffffff80, v16
	v_bitop3_b32 v16, v16, s22, v96 bitop3:0x36
	v_cndmask_b32_e32 v19, v20, v19, vcc
	v_and_b32_e32 v19, 0xffffff80, v19
	v_sub_u32_e32 v19, v19, v100
	v_add_u32_e32 v19, 0x7c, v19
	ds_write_b128 v138, v[16:19] offset:16384
	v_not_b32_e32 v16, v28
	v_or_b32_e32 v17, 0x80000000, v28
	v_cmp_gt_i32_e32 vcc, 0, v28
	v_and_b32_e32 v19, 0x7fffffff, v30
	v_and_b32_e32 v18, 0x7fffffff, v29
	v_cndmask_b32_e32 v16, v17, v16, vcc
	v_xor_b32_e32 v17, -1, v30
	v_pk_add_f32 v[18:19], v[18:19], 0 neg_lo:[1,1] neg_hi:[1,1]
	v_cmp_gt_i32_e32 vcc, 0, v30
	v_xor_b32_e32 v20, -1, v29
	v_mfma_f32_32x32x16_bf16 v[0:15], v[214:217], v[200:203], v[0:15]
	v_cndmask_b32_e32 v17, v19, v17, vcc
	v_cmp_gt_i32_e32 vcc, 0, v29
	v_and_b32_e32 v17, 0xffffff80, v17
	v_sub_u32_e32 v17, v17, v103
	v_cndmask_b32_e32 v18, v18, v20, vcc
	v_and_b32_e32 v18, 0xffffff80, v18
	v_sub_u32_e32 v19, v18, v102
	v_add_u32_e32 v18, 0x7d, v17
	v_add_u32_e32 v17, 0x7e, v19
	v_not_b32_e32 v19, v31
	v_or_b32_e32 v20, 0x80000000, v31
	v_cmp_gt_i32_e32 vcc, 0, v31
	v_and_b32_e32 v16, 0xffffff80, v16
	v_bitop3_b32 v16, v16, s23, v96 bitop3:0x36
	v_cndmask_b32_e32 v19, v20, v19, vcc
	v_and_b32_e32 v19, 0xffffff80, v19
	v_sub_u32_e32 v19, v19, v102
	v_add_u32_e32 v19, 0x7c, v19
	ds_write_b128 v139, v[16:19] offset:16384
	v_not_b32_e32 v16, v0
	v_or_b32_e32 v17, 0x80000000, v0
	v_cmp_gt_i32_e32 vcc, 0, v0
	v_xor_b32_e32 v18, -1, v2
	v_xor_b32_e32 v19, -1, v1
	v_cndmask_b32_e32 v0, v17, v16, vcc
	v_and_b32_e32 v17, 0x7fffffff, v2
	v_and_b32_e32 v16, 0x7fffffff, v1
	v_pk_add_f32 v[16:17], v[16:17], 0 neg_lo:[1,1] neg_hi:[1,1]
	v_cmp_gt_i32_e32 vcc, 0, v2
	v_and_b32_e32 v0, 0xffffff80, v0
	v_bitop3_b32 v0, v0, s16, v96 bitop3:0x36
	v_cndmask_b32_e32 v2, v17, v18, vcc
	v_cmp_gt_i32_e32 vcc, 0, v1
	v_or_b32_e32 v17, 0x80000000, v3
	v_and_b32_e32 v2, 0xffffff80, v2
	v_cndmask_b32_e32 v1, v16, v19, vcc
	v_not_b32_e32 v16, v3
	v_cmp_gt_i32_e32 vcc, 0, v3
	v_and_b32_e32 v1, 0xffffff80, v1
	v_sub_u32_e32 v1, v1, v104
	v_cndmask_b32_e32 v3, v17, v16, vcc
	v_and_b32_e32 v3, 0xffffff80, v3
	v_sub_u32_e32 v2, v2, v105
	v_sub_u32_e32 v3, v3, v104
	v_add_u32_e32 v2, 0x7d, v2
	v_add_u32_e32 v1, 0x7e, v1
	v_add_u32_e32 v3, 0x7c, v3
	ds_write_b128 v140, v[0:3] offset:16384
	v_not_b32_e32 v0, v4
	v_or_b32_e32 v1, 0x80000000, v4
	v_cmp_gt_i32_e32 vcc, 0, v4
	v_and_b32_e32 v3, 0x7fffffff, v6
	v_and_b32_e32 v2, 0x7fffffff, v5
	v_cndmask_b32_e32 v0, v1, v0, vcc
	v_xor_b32_e32 v1, -1, v6
	v_pk_add_f32 v[2:3], v[2:3], 0 neg_lo:[1,1] neg_hi:[1,1]
	v_cmp_gt_i32_e32 vcc, 0, v6
	v_xor_b32_e32 v4, -1, v5
	v_and_b32_e32 v0, 0xffffff80, v0
	v_cndmask_b32_e32 v1, v3, v1, vcc
	v_cmp_gt_i32_e32 vcc, 0, v5
	v_and_b32_e32 v1, 0xffffff80, v1
	v_sub_u32_e32 v1, v1, v107
	v_cndmask_b32_e32 v2, v2, v4, vcc
	v_and_b32_e32 v2, 0xffffff80, v2
	v_sub_u32_e32 v3, v2, v106
	v_add_u32_e32 v2, 0x7d, v1
	v_add_u32_e32 v1, 0x7e, v3
	v_not_b32_e32 v3, v7
	v_or_b32_e32 v4, 0x80000000, v7
	v_cmp_gt_i32_e32 vcc, 0, v7
	v_bitop3_b32 v0, v0, s24, v96 bitop3:0x36
	s_nop 0
	v_cndmask_b32_e32 v3, v4, v3, vcc
	v_and_b32_e32 v3, 0xffffff80, v3
	v_sub_u32_e32 v3, v3, v106
	v_add_u32_e32 v3, 0x7c, v3
	ds_write_b128 v141, v[0:3] offset:16384
	v_not_b32_e32 v0, v8
	v_or_b32_e32 v1, 0x80000000, v8
	v_cmp_gt_i32_e32 vcc, 0, v8
	v_and_b32_e32 v3, 0x7fffffff, v10
	v_and_b32_e32 v2, 0x7fffffff, v9
	v_cndmask_b32_e32 v0, v1, v0, vcc
	v_xor_b32_e32 v1, -1, v10
	v_pk_add_f32 v[2:3], v[2:3], 0 neg_lo:[1,1] neg_hi:[1,1]
	v_cmp_gt_i32_e32 vcc, 0, v10
	v_xor_b32_e32 v4, -1, v9
	v_and_b32_e32 v0, 0xffffff80, v0
	v_cndmask_b32_e32 v1, v3, v1, vcc
	v_cmp_gt_i32_e32 vcc, 0, v9
	v_and_b32_e32 v1, 0xffffff80, v1
	v_sub_u32_e32 v1, v1, v109
	v_cndmask_b32_e32 v2, v2, v4, vcc
	v_and_b32_e32 v2, 0xffffff80, v2
	v_sub_u32_e32 v3, v2, v108
	v_add_u32_e32 v2, 0x7d, v1
	v_add_u32_e32 v1, 0x7e, v3
	v_not_b32_e32 v3, v11
	v_or_b32_e32 v4, 0x80000000, v11
	v_cmp_gt_i32_e32 vcc, 0, v11
	v_bitop3_b32 v0, v0, s25, v96 bitop3:0x36
	s_nop 0
	v_cndmask_b32_e32 v3, v4, v3, vcc
	v_and_b32_e32 v3, 0xffffff80, v3
	v_sub_u32_e32 v3, v3, v108
	v_add_u32_e32 v3, 0x7c, v3
	ds_write_b128 v142, v[0:3] offset:16384
	v_not_b32_e32 v0, v12
	v_or_b32_e32 v1, 0x80000000, v12
	v_cmp_gt_i32_e32 vcc, 0, v12
	v_and_b32_e32 v3, 0x7fffffff, v14
	v_and_b32_e32 v2, 0x7fffffff, v13
	v_cndmask_b32_e32 v0, v1, v0, vcc
	v_xor_b32_e32 v1, -1, v14
	v_pk_add_f32 v[2:3], v[2:3], 0 neg_lo:[1,1] neg_hi:[1,1]
	v_cmp_gt_i32_e32 vcc, 0, v14
	v_xor_b32_e32 v4, -1, v13
	v_and_b32_e32 v0, 0xffffff80, v0
	v_cndmask_b32_e32 v1, v3, v1, vcc
	v_cmp_gt_i32_e32 vcc, 0, v13
	v_and_b32_e32 v1, 0xffffff80, v1
	v_sub_u32_e32 v1, v1, v111
	v_cndmask_b32_e32 v2, v2, v4, vcc
	v_and_b32_e32 v2, 0xffffff80, v2
	v_sub_u32_e32 v3, v2, v110
	v_add_u32_e32 v2, 0x7d, v1
	v_add_u32_e32 v1, 0x7e, v3
	v_not_b32_e32 v3, v15
	v_or_b32_e32 v4, 0x80000000, v15
	v_cmp_gt_i32_e32 vcc, 0, v15
	v_bitop3_b32 v0, v0, s26, v96 bitop3:0x36
	s_nop 0
	v_cndmask_b32_e32 v3, v4, v3, vcc
	v_and_b32_e32 v3, 0xffffff80, v3
	v_sub_u32_e32 v3, v3, v110
	v_add_u32_e32 v3, 0x7c, v3
	ds_write_b128 v143, v[0:3] offset:16384
	s_waitcnt lgkmcnt(0)
	s_barrier
	ds_read_b128 v[0:3], v144
	ds_read_b128 v[4:7], v145
	ds_read_b128 v[8:11], v146
	ds_read_b128 v[12:15], v147
	ds_read_b128 v[16:19], v149
	ds_read_b128 v[20:23], v150
	ds_read_b128 v[24:27], v151
	ds_read_b128 v[28:31], v159
	ds_read_b128 v[32:35], v161
	ds_read_b128 v[36:39], v163
	ds_read_b128 v[40:43], v172
	ds_read_b128 v[44:47], v173
	ds_read_b128 v[48:51], v174
	ds_read_b128 v[52:55], v175
	ds_read_b128 v[56:59], v176
	ds_read_b128 v[60:63], v177
	s_waitcnt lgkmcnt(0)
	s_barrier
	v_max_u32_e32 v212, v0, v1
	v_min_u32_e32 v1, v0, v1
	v_max_u32_e32 v0, v16, v17
	v_min_u32_e32 v17, v16, v17
	v_max_u32_e32 v16, v32, v33
	v_min_u32_e32 v33, v32, v33
	v_max_u32_e32 v32, v48, v49
	v_min_u32_e32 v49, v48, v49
	v_max_u32_e32 v48, v2, v3
	v_min_u32_e32 v3, v2, v3
	v_max_u32_e32 v2, v18, v19
	v_min_u32_e32 v19, v18, v19
	v_max_u32_e32 v18, v34, v35
	v_min_u32_e32 v35, v34, v35
	v_max_u32_e32 v34, v50, v51
	v_min_u32_e32 v51, v50, v51
	v_max_u32_e32 v50, v212, v48
	v_min_u32_e32 v48, v212, v48
	v_max_u32_e32 v212, v0, v2
	v_min_u32_e32 v2, v0, v2
	v_max_u32_e32 v0, v16, v18
	v_min_u32_e32 v18, v16, v18
	v_max_u32_e32 v16, v32, v34
	v_min_u32_e32 v34, v32, v34
	v_max_u32_e32 v32, v1, v3
	v_min_u32_e32 v3, v1, v3
	v_max_u32_e32 v1, v17, v19
	v_min_u32_e32 v19, v17, v19
	v_max_u32_e32 v17, v33, v35
	v_min_u32_e32 v35, v33, v35
	v_max_u32_e32 v33, v49, v51
	v_min_u32_e32 v51, v49, v51
	v_max_u32_e32 v49, v32, v48
	v_min_u32_e32 v48, v32, v48
	v_max_u32_e32 v32, v1, v2
	v_min_u32_e32 v2, v1, v2
	v_max_u32_e32 v1, v17, v18
	v_min_u32_e32 v18, v17, v18
	v_max_u32_e32 v17, v33, v34
	v_min_u32_e32 v34, v33, v34
	v_max_u32_e32 v33, v4, v5
	v_min_u32_e32 v5, v4, v5
	v_max_u32_e32 v4, v20, v21
	v_min_u32_e32 v21, v20, v21
	v_max_u32_e32 v20, v36, v37
	v_min_u32_e32 v37, v36, v37
	v_max_u32_e32 v36, v52, v53
	v_min_u32_e32 v53, v52, v53
	v_max_u32_e32 v52, v6, v7
	v_min_u32_e32 v7, v6, v7
	v_max_u32_e32 v6, v22, v23
	v_min_u32_e32 v23, v22, v23
	v_max_u32_e32 v22, v38, v39
	v_min_u32_e32 v39, v38, v39
	v_max_u32_e32 v38, v54, v55
	v_min_u32_e32 v55, v54, v55
	v_max_u32_e32 v54, v33, v52
	v_min_u32_e32 v52, v33, v52
	v_max_u32_e32 v33, v4, v6
	v_min_u32_e32 v6, v4, v6
	v_max_u32_e32 v4, v20, v22
	v_min_u32_e32 v22, v20, v22
	v_max_u32_e32 v20, v36, v38
	v_min_u32_e32 v38, v36, v38
	v_max_u32_e32 v36, v5, v7
	v_min_u32_e32 v7, v5, v7
	v_max_u32_e32 v5, v21, v23
	v_min_u32_e32 v23, v21, v23
	v_max_u32_e32 v21, v37, v39
	v_min_u32_e32 v39, v37, v39
	v_max_u32_e32 v37, v53, v55
	v_min_u32_e32 v55, v53, v55
	v_max_u32_e32 v53, v36, v52
	v_min_u32_e32 v52, v36, v52
	v_max_u32_e32 v36, v5, v6
	v_min_u32_e32 v6, v5, v6
	v_max_u32_e32 v5, v21, v22
	v_min_u32_e32 v22, v21, v22
	v_max_u32_e32 v21, v37, v38
	v_min_u32_e32 v38, v37, v38
	v_max_u32_e32 v37, v50, v54
	v_min_u32_e32 v54, v50, v54
	v_max_u32_e32 v50, v212, v33
	v_min_u32_e32 v33, v212, v33
	v_max_u32_e32 v212, v0, v4
	v_min_u32_e32 v4, v0, v4
	v_max_u32_e32 v0, v16, v20
	v_min_u32_e32 v20, v16, v20
	v_max_u32_e32 v16, v48, v52
	v_min_u32_e32 v52, v48, v52
	v_max_u32_e32 v48, v2, v6
	v_min_u32_e32 v6, v2, v6
	v_max_u32_e32 v2, v18, v22
	v_min_u32_e32 v22, v18, v22
	v_max_u32_e32 v18, v34, v38
	v_min_u32_e32 v38, v34, v38
	v_max_u32_e32 v34, v16, v54
	v_min_u32_e32 v54, v16, v54
	v_max_u32_e32 v16, v48, v33
	v_min_u32_e32 v33, v48, v33
	v_max_u32_e32 v48, v2, v4
	v_min_u32_e32 v4, v2, v4
	v_max_u32_e32 v2, v18, v20
	v_min_u32_e32 v20, v18, v20
	v_max_u32_e32 v18, v49, v53
	v_min_u32_e32 v53, v49, v53
	v_max_u32_e32 v49, v32, v36
	v_min_u32_e32 v36, v32, v36
	v_max_u32_e32 v32, v1, v5
	v_min_u32_e32 v5, v1, v5
	v_max_u32_e32 v1, v17, v21
	v_min_u32_e32 v21, v17, v21
	v_max_u32_e32 v17, v3, v7
	v_min_u32_e32 v7, v3, v7
	v_max_u32_e32 v3, v19, v23
	v_min_u32_e32 v23, v19, v23
	v_max_u32_e32 v19, v35, v39
	v_min_u32_e32 v39, v35, v39
	v_max_u32_e32 v35, v51, v55
	v_min_u32_e32 v55, v51, v55
	v_max_u32_e32 v51, v17, v53
	v_min_u32_e32 v53, v17, v53
	v_max_u32_e32 v17, v3, v36
	v_min_u32_e32 v36, v3, v36
	v_max_u32_e32 v3, v19, v5
	v_min_u32_e32 v5, v19, v5
	v_max_u32_e32 v19, v35, v21
	v_min_u32_e32 v21, v35, v21
	v_max_u32_e32 v35, v18, v34
	v_min_u32_e32 v34, v18, v34
	v_max_u32_e32 v18, v49, v16
	v_min_u32_e32 v16, v49, v16
	v_max_u32_e32 v49, v32, v48
	v_min_u32_e32 v48, v32, v48
	v_max_u32_e32 v32, v1, v2
	v_min_u32_e32 v2, v1, v2
	v_max_u32_e32 v1, v51, v54
	v_min_u32_e32 v54, v51, v54
	v_max_u32_e32 v51, v17, v33
	v_min_u32_e32 v33, v17, v33
	v_max_u32_e32 v17, v3, v4
	v_min_u32_e32 v4, v3, v4
	v_max_u32_e32 v3, v19, v20
	v_min_u32_e32 v20, v19, v20
	v_max_u32_e32 v19, v53, v52
	v_min_u32_e32 v52, v53, v52
	v_max_u32_e32 v53, v36, v6
	v_min_u32_e32 v6, v36, v6
	v_max_u32_e32 v36, v5, v22
	v_min_u32_e32 v22, v5, v22
	v_max_u32_e32 v5, v21, v38
	v_min_u32_e32 v38, v21, v38
	v_max_u32_e32 v21, v8, v9
	v_min_u32_e32 v9, v8, v9
	v_max_u32_e32 v8, v24, v25
	v_min_u32_e32 v25, v24, v25
	v_max_u32_e32 v24, v40, v41
	v_min_u32_e32 v41, v40, v41
	v_max_u32_e32 v40, v56, v57
	v_min_u32_e32 v57, v56, v57
	v_max_u32_e32 v56, v10, v11
	v_min_u32_e32 v11, v10, v11
	v_max_u32_e32 v10, v26, v27
	v_min_u32_e32 v27, v26, v27
	v_max_u32_e32 v26, v42, v43
	v_min_u32_e32 v43, v42, v43
	v_max_u32_e32 v42, v58, v59
	v_min_u32_e32 v59, v58, v59
	v_max_u32_e32 v58, v21, v56
	v_min_u32_e32 v56, v21, v56
	v_max_u32_e32 v21, v8, v10
	v_min_u32_e32 v10, v8, v10
	v_max_u32_e32 v8, v24, v26
	v_min_u32_e32 v26, v24, v26
	v_max_u32_e32 v24, v40, v42
	v_min_u32_e32 v42, v40, v42
	v_max_u32_e32 v40, v9, v11
	v_min_u32_e32 v11, v9, v11
	v_max_u32_e32 v9, v25, v27
	v_min_u32_e32 v27, v25, v27
	v_max_u32_e32 v25, v41, v43
	v_min_u32_e32 v43, v41, v43
	v_max_u32_e32 v41, v57, v59
	v_min_u32_e32 v59, v57, v59
	v_max_u32_e32 v57, v40, v56
	v_min_u32_e32 v56, v40, v56
	v_max_u32_e32 v40, v9, v10
	v_min_u32_e32 v10, v9, v10
	v_max_u32_e32 v9, v25, v26
	v_min_u32_e32 v26, v25, v26
	v_max_u32_e32 v25, v41, v42
	v_min_u32_e32 v42, v41, v42
	v_max_u32_e32 v41, v12, v13
	v_min_u32_e32 v13, v12, v13
	v_max_u32_e32 v12, v28, v29
	v_min_u32_e32 v29, v28, v29
	v_max_u32_e32 v28, v44, v45
	v_min_u32_e32 v45, v44, v45
	v_max_u32_e32 v44, v60, v61
	v_min_u32_e32 v61, v60, v61
	v_max_u32_e32 v60, v14, v15
	v_min_u32_e32 v15, v14, v15
	v_max_u32_e32 v14, v30, v31
	v_min_u32_e32 v31, v30, v31
	v_max_u32_e32 v30, v46, v47
	v_min_u32_e32 v47, v46, v47
	v_max_u32_e32 v46, v62, v63
	v_min_u32_e32 v63, v62, v63
	v_max_u32_e32 v62, v41, v60
	v_min_u32_e32 v60, v41, v60
	v_max_u32_e32 v41, v12, v14
	v_min_u32_e32 v14, v12, v14
	v_max_u32_e32 v12, v28, v30
	v_min_u32_e32 v30, v28, v30
	v_max_u32_e32 v28, v44, v46
	v_min_u32_e32 v46, v44, v46
	v_max_u32_e32 v44, v13, v15
	v_min_u32_e32 v15, v13, v15
	v_max_u32_e32 v13, v29, v31
	v_min_u32_e32 v31, v29, v31
	v_max_u32_e32 v29, v45, v47
	v_min_u32_e32 v47, v45, v47
	v_max_u32_e32 v45, v61, v63
	v_min_u32_e32 v63, v61, v63
	v_max_u32_e32 v61, v44, v60
	v_min_u32_e32 v60, v44, v60
	v_max_u32_e32 v44, v13, v14
	v_min_u32_e32 v14, v13, v14
	v_max_u32_e32 v13, v29, v30
	v_min_u32_e32 v30, v29, v30
	v_max_u32_e32 v29, v45, v46
	v_min_u32_e32 v46, v45, v46
	v_max_u32_e32 v45, v58, v62
	v_min_u32_e32 v62, v58, v62
	v_max_u32_e32 v58, v21, v41
	v_min_u32_e32 v41, v21, v41
	v_max_u32_e32 v21, v8, v12
	v_min_u32_e32 v12, v8, v12
	v_max_u32_e32 v8, v24, v28
	v_min_u32_e32 v28, v24, v28
	v_max_u32_e32 v24, v56, v60
	v_min_u32_e32 v60, v56, v60
	v_max_u32_e32 v56, v10, v14
	v_min_u32_e32 v14, v10, v14
	v_max_u32_e32 v10, v26, v30
	v_min_u32_e32 v30, v26, v30
	v_max_u32_e32 v26, v42, v46
	v_min_u32_e32 v46, v42, v46
	v_max_u32_e32 v42, v24, v62
	v_min_u32_e32 v62, v24, v62
	v_max_u32_e32 v24, v56, v41
	v_min_u32_e32 v41, v56, v41
	v_max_u32_e32 v56, v10, v12
	v_min_u32_e32 v12, v10, v12
	v_max_u32_e32 v10, v26, v28
	v_min_u32_e32 v28, v26, v28
	v_max_u32_e32 v26, v57, v61
	v_min_u32_e32 v61, v57, v61
	v_max_u32_e32 v57, v40, v44
	v_min_u32_e32 v44, v40, v44
	v_max_u32_e32 v40, v9, v13
	v_min_u32_e32 v13, v9, v13
	v_max_u32_e32 v9, v25, v29
	v_min_u32_e32 v29, v25, v29
	v_max_u32_e32 v25, v11, v15
	v_min_u32_e32 v15, v11, v15
	v_max_u32_e32 v11, v27, v31
	v_min_u32_e32 v31, v27, v31
	v_max_u32_e32 v27, v43, v47
	v_min_u32_e32 v47, v43, v47
	v_max_u32_e32 v43, v59, v63
	v_min_u32_e32 v63, v59, v63
	v_max_u32_e32 v59, v25, v61
	v_min_u32_e32 v61, v25, v61
	v_max_u32_e32 v25, v11, v44
	v_min_u32_e32 v44, v11, v44
	v_max_u32_e32 v11, v27, v13
	v_min_u32_e32 v13, v27, v13
	v_max_u32_e32 v27, v43, v29
	v_min_u32_e32 v29, v43, v29
	v_max_u32_e32 v43, v26, v42
	v_min_u32_e32 v42, v26, v42
	v_max_u32_e32 v26, v57, v24
	v_min_u32_e32 v24, v57, v24
	v_max_u32_e32 v57, v40, v56
	v_min_u32_e32 v56, v40, v56
	v_max_u32_e32 v40, v9, v10
	v_min_u32_e32 v10, v9, v10
	v_max_u32_e32 v9, v59, v62
	v_min_u32_e32 v62, v59, v62
	v_max_u32_e32 v59, v25, v41
	v_min_u32_e32 v41, v25, v41
	v_max_u32_e32 v25, v11, v12
	v_min_u32_e32 v12, v11, v12
	v_max_u32_e32 v11, v27, v28
	v_min_u32_e32 v28, v27, v28
	v_max_u32_e32 v27, v61, v60
	v_min_u32_e32 v60, v61, v60
	v_max_u32_e32 v61, v44, v14
	v_min_u32_e32 v14, v44, v14
	v_max_u32_e32 v44, v13, v30
	v_min_u32_e32 v30, v13, v30
	v_max_u32_e32 v13, v29, v46
	v_min_u32_e32 v46, v29, v46
	v_max_u32_e32 v29, v37, v45
	v_min_u32_e32 v45, v37, v45
	v_max_u32_e32 v37, v50, v58
	v_min_u32_e32 v58, v50, v58
	v_max_u32_e32 v50, v212, v21
	v_min_u32_e32 v21, v212, v21
	v_max_u32_e32 v212, v0, v8
	v_min_u32_e32 v8, v0, v8
	v_max_u32_e32 v0, v54, v62
	v_min_u32_e32 v62, v54, v62
	v_max_u32_e32 v54, v33, v41
	v_min_u32_e32 v41, v33, v41
	v_max_u32_e32 v33, v4, v12
	v_min_u32_e32 v12, v4, v12
	v_max_u32_e32 v4, v20, v28
	v_min_u32_e32 v28, v20, v28
	v_max_u32_e32 v20, v0, v45
	v_min_u32_e32 v45, v0, v45
	v_max_u32_e32 v0, v54, v58
	v_min_u32_e32 v58, v54, v58
	v_max_u32_e32 v54, v33, v21
	v_min_u32_e32 v21, v33, v21
	v_max_u32_e32 v33, v4, v8
	v_min_u32_e32 v8, v4, v8
	v_max_u32_e32 v4, v34, v42
	v_min_u32_e32 v42, v34, v42
	v_max_u32_e32 v34, v16, v24
	v_min_u32_e32 v24, v16, v24
	v_max_u32_e32 v16, v48, v56
	v_min_u32_e32 v56, v48, v56
	v_max_u32_e32 v48, v2, v10
	v_min_u32_e32 v10, v2, v10
	v_max_u32_e32 v2, v52, v60
	v_min_u32_e32 v60, v52, v60
	v_max_u32_e32 v52, v6, v14
	v_min_u32_e32 v14, v6, v14
	v_max_u32_e32 v6, v22, v30
	v_min_u32_e32 v30, v22, v30
	v_max_u32_e32 v22, v38, v46
	v_min_u32_e32 v46, v38, v46
	v_max_u32_e32 v38, v2, v42
	v_min_u32_e32 v42, v2, v42
	v_max_u32_e32 v2, v52, v24
	v_min_u32_e32 v24, v52, v24
	v_max_u32_e32 v52, v6, v56
	v_min_u32_e32 v56, v6, v56
	v_max_u32_e32 v6, v22, v10
	v_min_u32_e32 v10, v22, v10
	v_max_u32_e32 v22, v4, v20
	v_min_u32_e32 v20, v4, v20
	v_max_u32_e32 v4, v34, v0
	v_min_u32_e32 v0, v34, v0
	v_max_u32_e32 v34, v16, v54
	v_min_u32_e32 v54, v16, v54
	v_max_u32_e32 v16, v48, v33
	v_min_u32_e32 v33, v48, v33
	v_max_u32_e32 v48, v38, v45
	v_min_u32_e32 v45, v38, v45
	v_max_u32_e32 v38, v2, v58
	v_min_u32_e32 v58, v2, v58
	v_max_u32_e32 v2, v52, v21
	v_min_u32_e32 v21, v52, v21
	v_max_u32_e32 v52, v6, v8
	v_min_u32_e32 v8, v6, v8
	v_max_u32_e32 v6, v42, v62
	v_min_u32_e32 v62, v42, v62
	v_max_u32_e32 v42, v24, v41
	v_min_u32_e32 v41, v24, v41
	v_max_u32_e32 v24, v56, v12
	v_min_u32_e32 v12, v56, v12
	v_max_u32_e32 v56, v10, v28
	v_min_u32_e32 v28, v10, v28
	v_max_u32_e32 v10, v35, v43
	v_min_u32_e32 v43, v35, v43
	v_max_u32_e32 v35, v18, v26
	v_min_u32_e32 v26, v18, v26
	v_max_u32_e32 v18, v49, v57
	v_min_u32_e32 v57, v49, v57
	v_max_u32_e32 v49, v32, v40
	v_min_u32_e32 v40, v32, v40
	v_max_u32_e32 v32, v19, v27
	v_min_u32_e32 v27, v19, v27
	v_max_u32_e32 v19, v53, v61
	v_min_u32_e32 v61, v53, v61
	v_max_u32_e32 v53, v36, v44
	v_min_u32_e32 v44, v36, v44
	v_max_u32_e32 v36, v5, v13
	v_min_u32_e32 v13, v5, v13
	v_max_u32_e32 v5, v32, v43
	v_min_u32_e32 v43, v32, v43
	v_max_u32_e32 v32, v19, v26
	v_min_u32_e32 v26, v19, v26
	v_max_u32_e32 v19, v53, v57
	v_min_u32_e32 v57, v53, v57
	v_max_u32_e32 v53, v36, v40
	v_min_u32_e32 v40, v36, v40
	v_max_u32_e32 v36, v1, v9
	v_min_u32_e32 v9, v1, v9
	v_max_u32_e32 v1, v51, v59
	v_min_u32_e32 v59, v51, v59
	v_max_u32_e32 v51, v17, v25
	v_min_u32_e32 v25, v17, v25
	v_max_u32_e32 v17, v3, v11
	v_min_u32_e32 v11, v3, v11
	v_max_u32_e32 v3, v7, v15
	v_min_u32_e32 v15, v7, v15
	v_max_u32_e32 v7, v23, v31
	v_min_u32_e32 v31, v23, v31
	v_max_u32_e32 v23, v39, v47
	v_min_u32_e32 v47, v39, v47
	v_max_u32_e32 v39, v55, v63
	v_min_u32_e32 v63, v55, v63
	v_max_u32_e32 v55, v3, v9
	v_min_u32_e32 v9, v3, v9
	v_max_u32_e32 v3, v7, v59
	v_min_u32_e32 v59, v7, v59
	v_max_u32_e32 v7, v23, v25
	v_min_u32_e32 v25, v23, v25
	v_max_u32_e32 v23, v39, v11
	v_min_u32_e32 v11, v39, v11
	v_max_u32_e32 v39, v36, v5
	v_min_u32_e32 v5, v36, v5
	v_max_u32_e32 v36, v1, v32
	v_min_u32_e32 v32, v1, v32
	v_max_u32_e32 v1, v51, v19
	v_min_u32_e32 v19, v51, v19
	v_max_u32_e32 v51, v17, v53
	v_min_u32_e32 v53, v17, v53
	v_max_u32_e32 v17, v55, v43
	v_min_u32_e32 v43, v55, v43
	v_max_u32_e32 v55, v3, v26
	v_min_u32_e32 v26, v3, v26
	v_max_u32_e32 v3, v7, v57
	v_min_u32_e32 v57, v7, v57
	v_max_u32_e32 v7, v23, v40
	v_min_u32_e32 v40, v23, v40
	v_max_u32_e32 v23, v9, v27
	v_min_u32_e32 v27, v9, v27
	v_max_u32_e32 v9, v59, v61
	v_min_u32_e32 v61, v59, v61
	v_max_u32_e32 v59, v25, v44
	v_min_u32_e32 v44, v25, v44
	v_max_u32_e32 v25, v11, v13
	v_min_u32_e32 v13, v11, v13
	v_max_u32_e32 v11, v10, v22
	v_min_u32_e32 v22, v10, v22
	v_max_u32_e32 v10, v35, v4
	v_min_u32_e32 v4, v35, v4
	v_max_u32_e32 v35, v18, v34
	v_min_u32_e32 v34, v18, v34
	v_max_u32_e32 v18, v49, v16
	v_min_u32_e32 v16, v49, v16
	v_max_u32_e32 v49, v39, v20
	v_min_u32_e32 v20, v39, v20
	v_max_u32_e32 v39, v36, v0
	v_min_u32_e32 v0, v36, v0
	v_max_u32_e32 v36, v1, v54
	v_min_u32_e32 v54, v1, v54
	v_max_u32_e32 v1, v51, v33
	v_min_u32_e32 v33, v51, v33
	v_max_u32_e32 v51, v5, v48
	v_min_u32_e32 v48, v5, v48
	v_max_u32_e32 v5, v32, v38
	v_min_u32_e32 v38, v32, v38
	v_max_u32_e32 v32, v19, v2
	v_min_u32_e32 v2, v19, v2
	v_max_u32_e32 v19, v53, v52
	v_min_u32_e32 v52, v53, v52
	v_max_u32_e32 v53, v17, v45
	v_min_u32_e32 v45, v17, v45
	v_max_u32_e32 v17, v55, v58
	v_min_u32_e32 v58, v55, v58
	v_max_u32_e32 v55, v3, v21
	v_min_u32_e32 v21, v3, v21
	v_max_u32_e32 v3, v7, v8
	v_min_u32_e32 v8, v7, v8
	v_max_u32_e32 v7, v43, v6
	v_min_u32_e32 v6, v43, v6
	v_max_u32_e32 v43, v26, v42
	v_min_u32_e32 v42, v26, v42
	v_max_u32_e32 v26, v57, v24
	v_min_u32_e32 v24, v57, v24
	v_max_u32_e32 v57, v40, v56
	v_min_u32_e32 v56, v40, v56
	v_max_u32_e32 v40, v23, v62
	v_min_u32_e32 v62, v23, v62
	v_max_u32_e32 v23, v9, v41
	v_min_u32_e32 v41, v9, v41
	v_max_u32_e32 v9, v59, v12
	v_min_u32_e32 v12, v59, v12
	v_max_u32_e32 v59, v25, v28
	v_min_u32_e32 v28, v25, v28
	v_max_u32_e32 v25, v27, v60
	v_min_u32_e32 v60, v27, v60
	v_max_u32_e32 v27, v61, v14
	v_min_u32_e32 v14, v61, v14
	v_max_u32_e32 v61, v44, v30
	v_min_u32_e32 v30, v44, v30
	v_max_u32_e32 v44, v13, v46
	v_min_u32_e32 v46, v13, v46
	v_max_u32_e32 v29, v29, v31
	v_max_u32_e32 v11, v11, v14
	v_max_u32_e32 v22, v22, v27
	v_max_u32_e32 v49, v49, v41
	v_max_u32_e32 v20, v20, v23
	v_max_u32_e32 v51, v51, v42
	v_max_u32_e32 v48, v48, v43
	v_max_u32_e32 v53, v53, v58
	v_max_u32_e32 v45, v45, v17
	v_max_u32_e32 v7, v7, v38
	v_max_u32_e32 v6, v6, v5
	v_max_u32_e32 v40, v40, v0
	v_max_u32_e32 v62, v62, v39
	v_max_u32_e32 v25, v25, v4
	v_max_u32_e32 v60, v60, v10
	v_max_u32_e32 v15, v15, v37
	v_max_u32_e32 v13, v29, v45
	v_min_u32_e32 v45, v29, v45
	v_max_u32_e32 v29, v11, v7
	v_min_u32_e32 v7, v11, v7
	v_max_u32_e32 v11, v22, v6
	v_min_u32_e32 v6, v22, v6
	v_max_u32_e32 v22, v49, v40
	v_min_u32_e32 v40, v49, v40
	v_max_u32_e32 v49, v20, v62
	v_min_u32_e32 v62, v20, v62
	v_max_u32_e32 v20, v51, v25
	v_min_u32_e32 v25, v51, v25
	v_max_u32_e32 v51, v48, v60
	v_min_u32_e32 v60, v48, v60
	v_max_u32_e32 v48, v53, v15
	v_min_u32_e32 v15, v53, v15
	v_max_u32_e32 v53, v13, v49
	v_min_u32_e32 v49, v13, v49
	v_max_u32_e32 v13, v29, v20
	v_min_u32_e32 v20, v29, v20
	v_max_u32_e32 v29, v11, v51
	v_min_u32_e32 v51, v11, v51
	v_max_u32_e32 v11, v22, v48
	v_min_u32_e32 v48, v22, v48
	v_max_u32_e32 v22, v45, v62
	v_min_u32_e32 v62, v45, v62
	v_max_u32_e32 v45, v7, v25
	v_min_u32_e32 v25, v7, v25
	v_max_u32_e32 v7, v6, v60
	v_min_u32_e32 v60, v6, v60
	v_max_u32_e32 v6, v40, v15
	v_min_u32_e32 v15, v40, v15
	v_max_u32_e32 v40, v53, v29
	v_min_u32_e32 v29, v53, v29
	v_max_u32_e32 v53, v13, v11
	v_min_u32_e32 v11, v13, v11
	v_max_u32_e32 v13, v49, v51
	v_min_u32_e32 v51, v49, v51
	v_max_u32_e32 v49, v20, v48
	v_min_u32_e32 v48, v20, v48
	v_max_u32_e32 v20, v22, v7
	v_min_u32_e32 v7, v22, v7
	v_max_u32_e32 v22, v45, v6
	v_min_u32_e32 v6, v45, v6
	v_max_u32_e32 v45, v62, v60
	v_min_u32_e32 v60, v62, v60
	v_max_u32_e32 v62, v25, v15
	v_min_u32_e32 v15, v25, v15
	v_max_u32_e32 v25, v40, v53
	v_min_u32_e32 v53, v40, v53
	v_max_u32_e32 v40, v29, v11
	v_min_u32_e32 v11, v29, v11
	v_max_u32_e32 v29, v13, v49
	v_min_u32_e32 v49, v13, v49
	v_max_u32_e32 v13, v51, v48
	v_min_u32_e32 v48, v51, v48
	v_max_u32_e32 v51, v20, v22
	v_min_u32_e32 v22, v20, v22
	v_max_u32_e32 v20, v7, v6
	v_min_u32_e32 v6, v7, v6
	v_max_u32_e32 v7, v45, v62
	v_min_u32_e32 v62, v45, v62
	v_max_u32_e32 v45, v60, v15
	v_min_u32_e32 v15, v60, v15
	v_max_u32_e32 v50, v50, v63
	v_max_u32_e32 v35, v35, v46
	v_max_u32_e32 v34, v34, v44
	v_max_u32_e32 v36, v36, v28
	v_max_u32_e32 v54, v54, v59
	v_max_u32_e32 v32, v32, v56
	v_max_u32_e32 v2, v2, v57
	v_max_u32_e32 v55, v55, v8
	v_max_u32_e32 v21, v21, v3
	v_max_u32_e32 v26, v26, v52
	v_max_u32_e32 v24, v24, v19
	v_max_u32_e32 v9, v9, v33
	v_max_u32_e32 v12, v12, v1
	v_max_u32_e32 v61, v61, v16
	v_max_u32_e32 v30, v30, v18
	v_max_u32_e32 v47, v47, v212
	v_max_u32_e32 v60, v50, v21
	v_min_u32_e32 v21, v50, v21
	v_max_u32_e32 v50, v35, v26
	v_min_u32_e32 v26, v35, v26
	v_max_u32_e32 v35, v34, v24
	v_min_u32_e32 v24, v34, v24
	v_max_u32_e32 v34, v36, v9
	v_min_u32_e32 v9, v36, v9
	v_max_u32_e32 v36, v54, v12
	v_min_u32_e32 v12, v54, v12
	v_max_u32_e32 v54, v32, v61
	v_min_u32_e32 v61, v32, v61
	v_max_u32_e32 v32, v2, v30
	v_min_u32_e32 v30, v2, v30
	v_max_u32_e32 v2, v55, v47
	v_min_u32_e32 v47, v55, v47
	v_max_u32_e32 v55, v60, v36
	v_min_u32_e32 v36, v60, v36
	v_max_u32_e32 v60, v50, v54
	v_min_u32_e32 v54, v50, v54
	v_max_u32_e32 v50, v35, v32
	v_min_u32_e32 v32, v35, v32
	v_max_u32_e32 v35, v34, v2
	v_min_u32_e32 v2, v34, v2
	v_max_u32_e32 v34, v21, v12
	v_min_u32_e32 v12, v21, v12
	v_max_u32_e32 v21, v26, v61
	v_min_u32_e32 v61, v26, v61
	v_max_u32_e32 v26, v24, v30
	v_min_u32_e32 v30, v24, v30
	v_max_u32_e32 v24, v9, v47
	v_min_u32_e32 v47, v9, v47
	v_max_u32_e32 v9, v55, v50
	v_min_u32_e32 v50, v55, v50
	v_max_u32_e32 v55, v60, v35
	v_min_u32_e32 v35, v60, v35
	v_max_u32_e32 v60, v36, v32
	v_min_u32_e32 v32, v36, v32
	v_max_u32_e32 v36, v54, v2
	v_min_u32_e32 v2, v54, v2
	v_max_u32_e32 v54, v34, v26
	v_min_u32_e32 v26, v34, v26
	v_max_u32_e32 v34, v21, v24
	v_min_u32_e32 v24, v21, v24
	v_max_u32_e32 v21, v12, v30
	v_min_u32_e32 v30, v12, v30
	v_max_u32_e32 v12, v61, v47
	v_min_u32_e32 v47, v61, v47
	v_max_u32_e32 v61, v9, v55
	v_min_u32_e32 v55, v9, v55
	v_max_u32_e32 v9, v50, v35
	v_min_u32_e32 v35, v50, v35
	v_max_u32_e32 v50, v60, v36
	v_min_u32_e32 v36, v60, v36
	v_max_u32_e32 v60, v32, v2
	v_min_u32_e32 v2, v32, v2
	v_max_u32_e32 v32, v54, v34
	v_min_u32_e32 v34, v54, v34
	v_max_u32_e32 v54, v26, v24
	v_min_u32_e32 v24, v26, v24
	v_max_u32_e32 v26, v21, v12
	v_min_u32_e32 v12, v21, v12
	v_max_u32_e32 v21, v30, v47
	v_min_u32_e32 v47, v30, v47
	v_max_u32_e32 v25, v25, v47
	v_max_u32_e32 v53, v53, v21
	v_max_u32_e32 v40, v40, v12
	v_max_u32_e32 v11, v11, v26
	v_max_u32_e32 v29, v29, v24
	v_max_u32_e32 v49, v49, v54
	v_max_u32_e32 v13, v13, v34
	v_max_u32_e32 v48, v48, v32
	v_max_u32_e32 v51, v51, v2
	v_max_u32_e32 v22, v22, v60
	v_max_u32_e32 v20, v20, v36
	v_max_u32_e32 v6, v6, v50
	v_max_u32_e32 v7, v7, v35
	v_max_u32_e32 v62, v62, v9
	v_max_u32_e32 v45, v45, v55
	v_max_u32_e32 v15, v15, v61
	v_max_u32_e32 v30, v25, v51
	v_min_u32_e32 v51, v25, v51
	v_max_u32_e32 v25, v53, v22
	v_min_u32_e32 v22, v53, v22
	v_max_u32_e32 v53, v40, v20
	v_min_u32_e32 v20, v40, v20
	v_max_u32_e32 v40, v11, v6
	v_min_u32_e32 v6, v11, v6
	v_max_u32_e32 v11, v29, v7
	v_min_u32_e32 v7, v29, v7
	v_max_u32_e32 v29, v49, v62
	v_min_u32_e32 v62, v49, v62
	v_max_u32_e32 v49, v13, v45
	v_min_u32_e32 v45, v13, v45
	v_max_u32_e32 v13, v48, v15
	v_min_u32_e32 v15, v48, v15
	v_max_u32_e32 v48, v30, v11
	v_min_u32_e32 v11, v30, v11
	v_max_u32_e32 v30, v25, v29
	v_min_u32_e32 v29, v25, v29
	v_max_u32_e32 v25, v53, v49
	v_min_u32_e32 v49, v53, v49
	v_max_u32_e32 v53, v40, v13
	v_min_u32_e32 v13, v40, v13
	v_max_u32_e32 v40, v51, v7
	v_min_u32_e32 v7, v51, v7
	v_max_u32_e32 v51, v22, v62
	v_min_u32_e32 v62, v22, v62
	v_max_u32_e32 v22, v20, v45
	v_min_u32_e32 v45, v20, v45
	v_max_u32_e32 v20, v6, v15
	v_min_u32_e32 v15, v6, v15
	v_max_u32_e32 v6, v48, v25
	v_min_u32_e32 v25, v48, v25
	v_max_u32_e32 v48, v30, v53
	v_min_u32_e32 v53, v30, v53
	v_max_u32_e32 v30, v11, v49
	v_min_u32_e32 v49, v11, v49
	v_max_u32_e32 v11, v29, v13
	v_min_u32_e32 v13, v29, v13
	v_max_u32_e32 v29, v40, v22
	v_min_u32_e32 v22, v40, v22
	v_max_u32_e32 v40, v51, v20
	v_min_u32_e32 v20, v51, v20
	v_max_u32_e32 v51, v7, v45
	v_min_u32_e32 v45, v7, v45
	v_max_u32_e32 v7, v62, v15
	v_min_u32_e32 v15, v62, v15
	v_max_u32_e32 v62, v6, v48
	v_min_u32_e32 v48, v6, v48
	v_max_u32_e32 v6, v25, v53
	v_min_u32_e32 v53, v25, v53
	v_max_u32_e32 v25, v30, v11
	v_min_u32_e32 v11, v30, v11
	v_max_u32_e32 v30, v49, v13
	v_min_u32_e32 v13, v49, v13
	v_max_u32_e32 v49, v29, v40
	v_min_u32_e32 v40, v29, v40
	v_max_u32_e32 v29, v22, v20
	v_min_u32_e32 v20, v22, v20
	v_max_u32_e32 v22, v51, v7
	v_min_u32_e32 v7, v51, v7
	v_max_u32_e32 v51, v45, v15
	v_min_u32_e32 v15, v45, v15
	v_cmp_gt_i32_e32 vcc, 0, v62
	v_and_b32_e32 v213, 0x7fffff80, v62
	v_not_b32_e32 v214, v62
	v_or_b32_e32 v214, 0x7f, v214
	v_cndmask_b32_e32 v213, v214, v213, vcc
	v_not_b32_e32 v215, v62
	v_and_b32_e32 v215, 0x7f, v215
	ds_write_b32 v134, v213
	ds_write_b32 v134, v215 offset:16384
	v_cmp_gt_i32_e32 vcc, 0, v48
	v_and_b32_e32 v214, 0x7fffff80, v48
	v_not_b32_e32 v215, v48
	v_or_b32_e32 v215, 0x7f, v215
	v_cndmask_b32_e32 v214, v215, v214, vcc
	v_not_b32_e32 v213, v48
	v_and_b32_e32 v213, 0x7f, v213
	ds_write_b32 v134, v214 offset:1024
	ds_write_b32 v134, v213 offset:17408
	v_cmp_gt_i32_e32 vcc, 0, v6
	v_and_b32_e32 v215, 0x7fffff80, v6
	v_not_b32_e32 v213, v6
	v_or_b32_e32 v213, 0x7f, v213
	v_cndmask_b32_e32 v215, v213, v215, vcc
	v_not_b32_e32 v214, v6
	v_and_b32_e32 v214, 0x7f, v214
	ds_write_b32 v134, v215 offset:2048
	ds_write_b32 v134, v214 offset:18432
	v_cmp_gt_i32_e32 vcc, 0, v53
	v_and_b32_e32 v213, 0x7fffff80, v53
	v_not_b32_e32 v214, v53
	v_or_b32_e32 v214, 0x7f, v214
	v_cndmask_b32_e32 v213, v214, v213, vcc
	v_not_b32_e32 v215, v53
	v_and_b32_e32 v215, 0x7f, v215
	ds_write_b32 v134, v213 offset:3072
	ds_write_b32 v134, v215 offset:19456
	v_cmp_gt_i32_e32 vcc, 0, v25
	v_and_b32_e32 v214, 0x7fffff80, v25
	v_not_b32_e32 v215, v25
	v_or_b32_e32 v215, 0x7f, v215
	v_cndmask_b32_e32 v214, v215, v214, vcc
	v_not_b32_e32 v213, v25
	v_and_b32_e32 v213, 0x7f, v213
	ds_write_b32 v134, v214 offset:4096
	ds_write_b32 v134, v213 offset:20480
	v_cmp_gt_i32_e32 vcc, 0, v11
	v_and_b32_e32 v215, 0x7fffff80, v11
	v_not_b32_e32 v213, v11
	v_or_b32_e32 v213, 0x7f, v213
	v_cndmask_b32_e32 v215, v213, v215, vcc
	v_not_b32_e32 v214, v11
	v_and_b32_e32 v214, 0x7f, v214
	ds_write_b32 v134, v215 offset:5120
	ds_write_b32 v134, v214 offset:21504
	v_cmp_gt_i32_e32 vcc, 0, v30
	v_and_b32_e32 v213, 0x7fffff80, v30
	v_not_b32_e32 v214, v30
	v_or_b32_e32 v214, 0x7f, v214
	v_cndmask_b32_e32 v213, v214, v213, vcc
	v_not_b32_e32 v215, v30
	v_and_b32_e32 v215, 0x7f, v215
	ds_write_b32 v134, v213 offset:6144
	ds_write_b32 v134, v215 offset:22528
	v_cmp_gt_i32_e32 vcc, 0, v13
	v_and_b32_e32 v214, 0x7fffff80, v13
	v_not_b32_e32 v215, v13
	v_or_b32_e32 v215, 0x7f, v215
	v_cndmask_b32_e32 v214, v215, v214, vcc
	v_not_b32_e32 v213, v13
	v_and_b32_e32 v213, 0x7f, v213
	ds_write_b32 v134, v214 offset:7168
	ds_write_b32 v134, v213 offset:23552
	v_cmp_gt_i32_e32 vcc, 0, v49
	v_and_b32_e32 v215, 0x7fffff80, v49
	v_not_b32_e32 v213, v49
	v_or_b32_e32 v213, 0x7f, v213
	v_cndmask_b32_e32 v215, v213, v215, vcc
	v_not_b32_e32 v214, v49
	v_and_b32_e32 v214, 0x7f, v214
	ds_write_b32 v134, v215 offset:8192
	ds_write_b32 v134, v214 offset:24576
	v_cmp_gt_i32_e32 vcc, 0, v40
	v_and_b32_e32 v213, 0x7fffff80, v40
	v_not_b32_e32 v214, v40
	v_or_b32_e32 v214, 0x7f, v214
	v_cndmask_b32_e32 v213, v214, v213, vcc
	v_not_b32_e32 v215, v40
	v_and_b32_e32 v215, 0x7f, v215
	ds_write_b32 v134, v213 offset:9216
	ds_write_b32 v134, v215 offset:25600
	v_cmp_gt_i32_e32 vcc, 0, v29
	v_and_b32_e32 v214, 0x7fffff80, v29
	v_not_b32_e32 v215, v29
	v_or_b32_e32 v215, 0x7f, v215
	v_cndmask_b32_e32 v214, v215, v214, vcc
	v_not_b32_e32 v213, v29
	v_and_b32_e32 v213, 0x7f, v213
	ds_write_b32 v134, v214 offset:10240
	ds_write_b32 v134, v213 offset:26624
	v_cmp_gt_i32_e32 vcc, 0, v20
	v_and_b32_e32 v215, 0x7fffff80, v20
	v_not_b32_e32 v213, v20
	v_or_b32_e32 v213, 0x7f, v213
	v_cndmask_b32_e32 v215, v213, v215, vcc
	v_not_b32_e32 v214, v20
	v_and_b32_e32 v214, 0x7f, v214
	ds_write_b32 v134, v215 offset:11264
	ds_write_b32 v134, v214 offset:27648
	v_cmp_gt_i32_e32 vcc, 0, v22
	v_and_b32_e32 v213, 0x7fffff80, v22
	v_not_b32_e32 v214, v22
	v_or_b32_e32 v214, 0x7f, v214
	v_cndmask_b32_e32 v213, v214, v213, vcc
	v_not_b32_e32 v215, v22
	v_and_b32_e32 v215, 0x7f, v215
	ds_write_b32 v134, v213 offset:12288
	ds_write_b32 v134, v215 offset:28672
	v_cmp_gt_i32_e32 vcc, 0, v7
	v_and_b32_e32 v214, 0x7fffff80, v7
	v_not_b32_e32 v215, v7
	v_or_b32_e32 v215, 0x7f, v215
	v_cndmask_b32_e32 v214, v215, v214, vcc
	v_not_b32_e32 v213, v7
	v_and_b32_e32 v213, 0x7f, v213
	ds_write_b32 v134, v214 offset:13312
	ds_write_b32 v134, v213 offset:29696
	v_cmp_gt_i32_e32 vcc, 0, v51
	v_and_b32_e32 v215, 0x7fffff80, v51
	v_not_b32_e32 v213, v51
	v_or_b32_e32 v213, 0x7f, v213
	v_cndmask_b32_e32 v215, v213, v215, vcc
	v_not_b32_e32 v214, v51
	v_and_b32_e32 v214, 0x7f, v214
	ds_write_b32 v134, v215 offset:14336
	ds_write_b32 v134, v214 offset:30720
	v_cmp_gt_i32_e32 vcc, 0, v15
	v_and_b32_e32 v213, 0x7fffff80, v15
	v_not_b32_e32 v214, v15
	v_or_b32_e32 v214, 0x7f, v214
	v_cndmask_b32_e32 v213, v214, v213, vcc
	v_not_b32_e32 v215, v15
	v_and_b32_e32 v215, 0x7f, v215
	ds_write_b32 v134, v213 offset:15360
	ds_write_b32 v134, v215 offset:31744
	s_waitcnt lgkmcnt(0)
	s_barrier
	s_and_saveexec_b64 s[8:9], s[12:13]
	s_cbranch_execz .LBB0_621
	s_and_b64 s[14:15], s[4:5], exec
	s_cselect_b32 s2, s17, s27
	s_cselect_b32 s14, s18, s28
	v_add_u32_e32 v0, s14, v156
	v_add_u32_e32 v1, s2, v162
	s_mov_b32 s2, 0
	v_mov_b32_e32 v2, 0
	v_mov_b32_e32 v3, 0

.LBB0_1084:
	s_or_b32 s8, s0, s57
	s_lshl_b32 s8, s8, 15
	s_add_u32 s8, s66, s8
	s_addc_u32 s9, s67, 0
	s_lshl_b32 s0, s0, 8
	s_or_b32 s0, s0, s58
	v_lshl_add_u64 v[16:17], v[66:67], 0, s[0:1]
	v_lshl_add_u64 v[0:1], s[8:9], 0, v[64:65]
	v_mov_b32_e32 v85, v65
	v_mov_b32_e32 v87, v65
	v_mov_b32_e32 v89, v65
	v_mov_b32_e32 v91, v65
	v_lshl_add_u64 v[32:33], v[16:17], 0, v[92:93]
	v_lshl_add_u64 v[8:9], v[0:1], 0, v[84:85]
	v_lshl_add_u64 v[12:13], v[0:1], 0, v[86:87]
	v_lshl_add_u64 v[2:3], v[0:1], 0, v[88:89]
	v_lshl_add_u64 v[4:5], v[0:1], 0, v[90:91]
	v_lshl_add_u64 v[34:35], v[16:17], 0, v[94:95]
	v_lshl_add_u64 v[36:37], v[16:17], 0, v[96:97]
	global_load_dwordx4 v[0:3], v[2:3], off
	s_nop 0
	global_load_dwordx4 v[4:7], v[4:5], off
	s_nop 0
	global_load_dwordx4 v[8:11], v[8:9], off
	s_nop 0
	global_load_dwordx4 v[12:15], v[12:13], off
	v_lshl_add_u64 v[38:39], v[16:17], 0, v[98:99]
	global_load_dwordx4 v[16:19], v[32:33], off
	global_load_dwordx4 v[20:23], v[34:35], off
	global_load_dwordx4 v[24:27], v[36:37], off
	global_load_dwordx4 v[28:31], v[38:39], off
	v_lshl_add_u64 v[40:41], s[8:9], 0, v[84:85]
	v_lshl_add_u64 v[42:43], s[8:9], 0, v[86:87]
	v_lshl_add_u64 v[44:45], s[8:9], 0, v[88:89]
	v_lshl_add_u64 v[46:47], s[8:9], 0, v[90:91]
	v_lshl_add_u64 v[40:41], v[40:41], 0, v[64:65]
	v_lshl_add_u64 v[42:43], v[42:43], 0, v[64:65]
	v_lshl_add_u64 v[44:45], v[44:45], 0, v[64:65]
	v_lshl_add_u64 v[46:47], v[46:47], 0, v[64:65]
	s_barrier
	s_waitcnt vmcnt(6)
	ds_write_b128 v100, v[4:7] offset:18432
	ds_write_b128 v100, v[0:3] offset:23040
	s_waitcnt vmcnt(4)
	ds_write_b128 v100, v[12:15] offset:27648
	ds_write_b128 v100, v[8:11] offset:32256
	s_waitcnt vmcnt(3)
	ds_write_b128 v100, v[16:19]
	s_waitcnt vmcnt(2)
	ds_write_b128 v100, v[20:23] offset:4608
	s_waitcnt vmcnt(1)
	ds_write_b128 v100, v[24:27] offset:9216
	s_waitcnt vmcnt(0)
	ds_write_b128 v100, v[28:31] offset:13824
	s_waitcnt lgkmcnt(0)
	s_barrier
	global_load_dwordx4 v[134:137], v[32:33], off offset:128
	global_load_dwordx4 v[138:141], v[34:35], off offset:128
	global_load_dwordx4 v[142:145], v[36:37], off offset:128
	global_load_dwordx4 v[146:149], v[38:39], off offset:128
	global_load_dwordx4 v[164:167], v[40:41], off offset:128
	global_load_dwordx4 v[186:189], v[42:43], off offset:128
	global_load_dwordx4 v[190:193], v[44:45], off offset:128
	global_load_dwordx4 v[194:197], v[46:47], off offset:128
	ds_read_b128 v[0:3], v102 offset:18432
	ds_read_b128 v[4:7], v101
	ds_read_b128 v[198:201], v101 offset:32
	ds_read_b128 v[202:205], v102 offset:18464
	ds_read_b128 v[8:11], v102 offset:23040
	ds_read_b128 v[212:215], v102 offset:23072
	s_waitcnt lgkmcnt(4)
	v_mfma_f32_32x32x16_bf16 v[48:63], v[0:3], v[4:7], 0
	s_waitcnt lgkmcnt(1)
	v_mfma_f32_32x32x16_bf16 v[32:47], v[8:11], v[4:7], 0
	ds_read_b128 v[4:7], v101 offset:4608
	ds_read_b128 v[216:219], v101 offset:4640
	s_waitcnt lgkmcnt(1)
	v_mfma_f32_32x32x16_bf16 v[16:31], v[0:3], v[4:7], 0
	v_mfma_f32_32x32x16_bf16 v[0:15], v[8:11], v[4:7], 0
	v_mfma_f32_32x32x16_bf16 v[48:63], v[202:205], v[198:201], v[48:63]
	v_mfma_f32_32x32x16_bf16 v[32:47], v[212:215], v[198:201], v[32:47]
	s_waitcnt lgkmcnt(0)
	v_mfma_f32_32x32x16_bf16 v[16:31], v[202:205], v[216:219], v[16:31]
	v_mfma_f32_32x32x16_bf16 v[0:15], v[212:215], v[216:219], v[0:15]
	ds_read_b128 v[198:201], v102 offset:18496
	ds_read_b128 v[202:205], v101 offset:64
	ds_read_b128 v[212:215], v101 offset:96
	ds_read_b128 v[216:219], v102 offset:18528
	ds_read_b128 v[220:223], v102 offset:23104
	ds_read_b128 v[224:227], v102 offset:23136
	s_waitcnt lgkmcnt(4)
	v_mfma_f32_32x32x16_bf16 v[48:63], v[198:201], v[202:205], v[48:63]
	s_waitcnt lgkmcnt(1)
	v_mfma_f32_32x32x16_bf16 v[32:47], v[220:223], v[202:205], v[32:47]
	ds_read_b128 v[202:205], v101 offset:4672
	ds_read_b128 v[228:231], v101 offset:4704
	s_waitcnt lgkmcnt(0)
	s_barrier
	s_waitcnt vmcnt(7)
	ds_write_b128 v100, v[134:137]
	s_waitcnt vmcnt(0)
	ds_write_b128 v100, v[194:197] offset:18432
	ds_write_b128 v100, v[138:141] offset:4608
	ds_write_b128 v100, v[190:193] offset:23040
	ds_write_b128 v100, v[142:145] offset:9216
	ds_write_b128 v100, v[186:189] offset:27648
	ds_write_b128 v100, v[146:149] offset:13824
	ds_write_b128 v100, v[164:167] offset:32256
	s_waitcnt lgkmcnt(0)
	v_mfma_f32_32x32x16_bf16 v[16:31], v[198:201], v[202:205], v[16:31]
	s_barrier
	v_mfma_f32_32x32x16_bf16 v[0:15], v[220:223], v[202:205], v[0:15]
	v_mfma_f32_32x32x16_bf16 v[48:63], v[216:219], v[212:215], v[48:63]
	v_mfma_f32_32x32x16_bf16 v[32:47], v[224:227], v[212:215], v[32:47]
	v_mfma_f32_32x32x16_bf16 v[16:31], v[216:219], v[228:231], v[16:31]
	v_mfma_f32_32x32x16_bf16 v[0:15], v[224:227], v[228:231], v[0:15]
	ds_read_b128 v[134:137], v102 offset:18432
	ds_read_b128 v[138:141], v101
	ds_read_b128 v[142:145], v101 offset:32
	ds_read_b128 v[146:149], v102 offset:18464
	ds_read_b128 v[164:167], v102 offset:23040
	ds_read_b128 v[186:189], v102 offset:23072
	s_waitcnt lgkmcnt(4)
	v_mfma_f32_32x32x16_bf16 v[48:63], v[134:137], v[138:141], v[48:63]
	s_waitcnt lgkmcnt(2)
	v_mfma_f32_32x32x16_bf16 v[48:63], v[146:149], v[142:145], v[48:63]
	s_waitcnt lgkmcnt(1)
	v_mfma_f32_32x32x16_bf16 v[32:47], v[164:167], v[138:141], v[32:47]
	ds_read_b128 v[138:141], v102 offset:18496
	ds_read_b128 v[190:193], v101 offset:64
	ds_read_b128 v[194:197], v101 offset:4608
	ds_read_b128 v[198:201], v101 offset:4640
	ds_read_b128 v[202:205], v101 offset:96
	ds_read_b128 v[212:215], v102 offset:18528
	ds_read_b128 v[216:219], v101 offset:4672
	ds_read_b128 v[220:223], v101 offset:4704
	ds_read_b128 v[224:227], v102 offset:23104
	ds_read_b128 v[228:231], v102 offset:23136
	s_waitcnt lgkmcnt(0)
	s_barrier
	v_mfma_f32_32x32x16_bf16 v[48:63], v[138:141], v[190:193], v[48:63]
	v_mfma_f32_32x32x16_bf16 v[48:63], v[212:215], v[202:205], v[48:63]
	v_mfma_f32_32x32x16_bf16 v[32:47], v[186:189], v[142:145], v[32:47]
	s_nop 10
	v_not_b32_e32 v85, v48
	v_or_b32_e32 v87, 0x80000000, v48
	v_and_b32_e32 v151, 0x7fffffff, v50
	v_and_b32_e32 v150, 0x7fffffff, v49
	v_cmp_gt_i32_e32 vcc, 0, v48
	v_xor_b32_e32 v89, -1, v50
	v_pk_add_f32 v[150:151], v[150:151], 0 neg_lo:[1,1] neg_hi:[1,1]
	v_cndmask_b32_e32 v48, v87, v85, vcc
	v_cmp_gt_i32_e32 vcc, 0, v50
	v_xor_b32_e32 v91, -1, v49
	v_not_b32_e32 v85, v51
	v_cndmask_b32_e32 v50, v151, v89, vcc
	v_cmp_gt_i32_e32 vcc, 0, v49
	v_or_b32_e32 v87, 0x80000000, v51
	v_and_b32_e32 v50, 0xffffff80, v50
	v_cndmask_b32_e32 v49, v150, v91, vcc
	v_cmp_gt_i32_e32 vcc, 0, v51
	v_and_b32_e32 v49, 0xffffff80, v49
	v_and_b32_e32 v48, 0xffffff80, v48
	v_cndmask_b32_e32 v51, v87, v85, vcc
	v_and_b32_e32 v51, 0xffffff80, v51
	v_sub_u32_e32 v49, v49, v68
	v_sub_u32_e32 v50, v50, v69
	v_sub_u32_e32 v51, v51, v68
	v_bitop3_b32 v48, v48, s25, v68 bitop3:0x36
	v_add_u32_e32 v50, 0x7d, v50
	v_add_u32_e32 v49, 0x7e, v49
	v_add_u32_e32 v51, 0x7c, v51
	ds_write_b128 v108, v[48:51]
	v_not_b32_e32 v48, v52
	v_or_b32_e32 v49, 0x80000000, v52
	v_cmp_gt_i32_e32 vcc, 0, v52
	v_and_b32_e32 v51, 0x7fffffff, v54
	v_and_b32_e32 v50, 0x7fffffff, v53
	v_cndmask_b32_e32 v48, v49, v48, vcc
	v_xor_b32_e32 v49, -1, v54
	v_pk_add_f32 v[50:51], v[50:51], 0 neg_lo:[1,1] neg_hi:[1,1]
	v_cmp_gt_i32_e32 vcc, 0, v54
	v_xor_b32_e32 v52, -1, v53
	v_and_b32_e32 v48, 0xffffff80, v48
	v_cndmask_b32_e32 v49, v51, v49, vcc
	v_cmp_gt_i32_e32 vcc, 0, v53
	v_and_b32_e32 v49, 0xffffff80, v49
	v_sub_u32_e32 v49, v49, v71
	v_cndmask_b32_e32 v50, v50, v52, vcc
	v_and_b32_e32 v50, 0xffffff80, v50
	v_sub_u32_e32 v51, v50, v70
	v_add_u32_e32 v50, 0x7d, v49
	v_add_u32_e32 v49, 0x7e, v51
	v_not_b32_e32 v51, v55
	v_or_b32_e32 v52, 0x80000000, v55
	v_cmp_gt_i32_e32 vcc, 0, v55
	v_bitop3_b32 v48, v48, s27, v68 bitop3:0x36
	v_mfma_f32_32x32x16_bf16 v[32:47], v[224:227], v[190:193], v[32:47]
	v_cndmask_b32_e32 v51, v52, v51, vcc
	v_and_b32_e32 v51, 0xffffff80, v51
	v_sub_u32_e32 v51, v51, v70
	v_add_u32_e32 v51, 0x7c, v51
	ds_write_b128 v109, v[48:51]
	v_not_b32_e32 v48, v56
	v_or_b32_e32 v49, 0x80000000, v56
	v_cmp_gt_i32_e32 vcc, 0, v56
	v_and_b32_e32 v51, 0x7fffffff, v58
	v_and_b32_e32 v50, 0x7fffffff, v57
	v_cndmask_b32_e32 v48, v49, v48, vcc
	v_xor_b32_e32 v49, -1, v58
	v_pk_add_f32 v[50:51], v[50:51], 0 neg_lo:[1,1] neg_hi:[1,1]
	v_cmp_gt_i32_e32 vcc, 0, v58
	v_xor_b32_e32 v52, -1, v57
	v_and_b32_e32 v48, 0xffffff80, v48
	v_cndmask_b32_e32 v49, v51, v49, vcc
	v_cmp_gt_i32_e32 vcc, 0, v57
	v_and_b32_e32 v49, 0xffffff80, v49
	v_sub_u32_e32 v49, v49, v73
	v_cndmask_b32_e32 v50, v50, v52, vcc
	v_and_b32_e32 v50, 0xffffff80, v50
	v_sub_u32_e32 v51, v50, v72
	v_add_u32_e32 v50, 0x7d, v49
	v_add_u32_e32 v49, 0x7e, v51
	v_not_b32_e32 v51, v59
	v_or_b32_e32 v52, 0x80000000, v59
	v_cmp_gt_i32_e32 vcc, 0, v59
	v_bitop3_b32 v48, v48, s28, v68 bitop3:0x36
	v_mfma_f32_32x32x16_bf16 v[32:47], v[228:231], v[202:205], v[32:47]
	v_cndmask_b32_e32 v51, v52, v51, vcc
	v_and_b32_e32 v51, 0xffffff80, v51
	v_sub_u32_e32 v51, v51, v72
	v_add_u32_e32 v51, 0x7c, v51
	ds_write_b128 v110, v[48:51]
	v_not_b32_e32 v48, v60
	v_or_b32_e32 v49, 0x80000000, v60
	v_cmp_gt_i32_e32 vcc, 0, v60
	v_and_b32_e32 v51, 0x7fffffff, v62
	v_and_b32_e32 v50, 0x7fffffff, v61
	v_cndmask_b32_e32 v48, v49, v48, vcc
	v_xor_b32_e32 v49, -1, v62
	v_pk_add_f32 v[50:51], v[50:51], 0 neg_lo:[1,1] neg_hi:[1,1]
	v_cmp_gt_i32_e32 vcc, 0, v62
	v_xor_b32_e32 v52, -1, v61
	v_and_b32_e32 v48, 0xffffff80, v48
	v_cndmask_b32_e32 v49, v51, v49, vcc
	v_cmp_gt_i32_e32 vcc, 0, v61
	v_and_b32_e32 v49, 0xffffff80, v49
	v_sub_u32_e32 v49, v49, v75
	v_cndmask_b32_e32 v50, v50, v52, vcc
	v_and_b32_e32 v50, 0xffffff80, v50
	v_sub_u32_e32 v51, v50, v74
	v_add_u32_e32 v50, 0x7d, v49
	v_add_u32_e32 v49, 0x7e, v51
	v_not_b32_e32 v51, v63
	v_or_b32_e32 v52, 0x80000000, v63
	v_cmp_gt_i32_e32 vcc, 0, v63
	v_bitop3_b32 v48, v48, s29, v68 bitop3:0x36
	v_mfma_f32_32x32x16_bf16 v[16:31], v[134:137], v[194:197], v[16:31]
	v_cndmask_b32_e32 v51, v52, v51, vcc
	v_and_b32_e32 v51, 0xffffff80, v51
	v_sub_u32_e32 v51, v51, v74
	v_add_u32_e32 v51, 0x7c, v51
	ds_write_b128 v111, v[48:51]
	v_not_b32_e32 v48, v32
	v_or_b32_e32 v49, 0x80000000, v32
	v_cmp_gt_i32_e32 vcc, 0, v32
	v_xor_b32_e32 v50, -1, v34
	v_xor_b32_e32 v51, -1, v33
	v_cndmask_b32_e32 v32, v49, v48, vcc
	v_and_b32_e32 v49, 0x7fffffff, v34
	v_and_b32_e32 v48, 0x7fffffff, v33
	v_pk_add_f32 v[48:49], v[48:49], 0 neg_lo:[1,1] neg_hi:[1,1]
	v_cmp_gt_i32_e32 vcc, 0, v34
	v_and_b32_e32 v32, 0xffffff80, v32
	v_bitop3_b32 v32, v32, s22, v68 bitop3:0x36
	v_cndmask_b32_e32 v34, v49, v50, vcc
	v_cmp_gt_i32_e32 vcc, 0, v33
	v_or_b32_e32 v49, 0x80000000, v35
	v_and_b32_e32 v34, 0xffffff80, v34
	v_cndmask_b32_e32 v33, v48, v51, vcc
	v_not_b32_e32 v48, v35
	v_cmp_gt_i32_e32 vcc, 0, v35
	v_and_b32_e32 v33, 0xffffff80, v33
	v_sub_u32_e32 v33, v33, v76
	v_cndmask_b32_e32 v35, v49, v48, vcc
	v_and_b32_e32 v35, 0xffffff80, v35
	v_sub_u32_e32 v34, v34, v77
	v_sub_u32_e32 v35, v35, v76
	v_add_u32_e32 v34, 0x7d, v34
	v_add_u32_e32 v33, 0x7e, v33
	v_add_u32_e32 v35, 0x7c, v35
	ds_write_b128 v112, v[32:35]
	v_not_b32_e32 v32, v36
	v_or_b32_e32 v33, 0x80000000, v36
	v_cmp_gt_i32_e32 vcc, 0, v36
	v_and_b32_e32 v35, 0x7fffffff, v38
	v_and_b32_e32 v34, 0x7fffffff, v37
	v_cndmask_b32_e32 v32, v33, v32, vcc
	v_xor_b32_e32 v33, -1, v38
	v_pk_add_f32 v[34:35], v[34:35], 0 neg_lo:[1,1] neg_hi:[1,1]
	v_cmp_gt_i32_e32 vcc, 0, v38
	v_xor_b32_e32 v36, -1, v37
	v_mfma_f32_32x32x16_bf16 v[16:31], v[146:149], v[198:201], v[16:31]
	v_cndmask_b32_e32 v33, v35, v33, vcc
	v_cmp_gt_i32_e32 vcc, 0, v37
	v_and_b32_e32 v33, 0xffffff80, v33
	v_sub_u32_e32 v33, v33, v79
	v_cndmask_b32_e32 v34, v34, v36, vcc
	v_and_b32_e32 v34, 0xffffff80, v34
	v_sub_u32_e32 v35, v34, v78
	v_add_u32_e32 v34, 0x7d, v33
	v_add_u32_e32 v33, 0x7e, v35
	v_not_b32_e32 v35, v39
	v_or_b32_e32 v36, 0x80000000, v39
	v_cmp_gt_i32_e32 vcc, 0, v39
	v_and_b32_e32 v32, 0xffffff80, v32
	v_bitop3_b32 v32, v32, s35, v68 bitop3:0x36
	v_cndmask_b32_e32 v35, v36, v35, vcc
	v_and_b32_e32 v35, 0xffffff80, v35
	v_sub_u32_e32 v35, v35, v78
	v_add_u32_e32 v35, 0x7c, v35
	ds_write_b128 v113, v[32:35]
	v_not_b32_e32 v32, v40
	v_or_b32_e32 v33, 0x80000000, v40
	v_cmp_gt_i32_e32 vcc, 0, v40
	v_and_b32_e32 v35, 0x7fffffff, v42
	v_and_b32_e32 v34, 0x7fffffff, v41
	v_cndmask_b32_e32 v32, v33, v32, vcc
	v_xor_b32_e32 v33, -1, v42
	v_pk_add_f32 v[34:35], v[34:35], 0 neg_lo:[1,1] neg_hi:[1,1]
	v_cmp_gt_i32_e32 vcc, 0, v42
	v_xor_b32_e32 v36, -1, v41
	v_mfma_f32_32x32x16_bf16 v[16:31], v[138:141], v[216:219], v[16:31]
	v_cndmask_b32_e32 v33, v35, v33, vcc
	v_cmp_gt_i32_e32 vcc, 0, v41
	v_and_b32_e32 v33, 0xffffff80, v33
	v_sub_u32_e32 v33, v33, v81
	v_cndmask_b32_e32 v34, v34, v36, vcc
	v_and_b32_e32 v34, 0xffffff80, v34
	v_sub_u32_e32 v35, v34, v80
	v_add_u32_e32 v34, 0x7d, v33
	v_add_u32_e32 v33, 0x7e, v35
	v_not_b32_e32 v35, v43
	v_or_b32_e32 v36, 0x80000000, v43
	v_cmp_gt_i32_e32 vcc, 0, v43
	v_and_b32_e32 v32, 0xffffff80, v32
	v_bitop3_b32 v32, v32, s40, v68 bitop3:0x36
	v_cndmask_b32_e32 v35, v36, v35, vcc
	v_and_b32_e32 v35, 0xffffff80, v35
	v_sub_u32_e32 v35, v35, v80
	v_add_u32_e32 v35, 0x7c, v35
	ds_write_b128 v114, v[32:35]
	v_not_b32_e32 v32, v44
	v_or_b32_e32 v33, 0x80000000, v44
	v_cmp_gt_i32_e32 vcc, 0, v44
	v_and_b32_e32 v35, 0x7fffffff, v46
	v_and_b32_e32 v34, 0x7fffffff, v45
	v_cndmask_b32_e32 v32, v33, v32, vcc
	v_xor_b32_e32 v33, -1, v46
	v_pk_add_f32 v[34:35], v[34:35], 0 neg_lo:[1,1] neg_hi:[1,1]
	v_cmp_gt_i32_e32 vcc, 0, v46
	v_xor_b32_e32 v36, -1, v45
	v_mfma_f32_32x32x16_bf16 v[16:31], v[212:215], v[220:223], v[16:31]
	v_cndmask_b32_e32 v33, v35, v33, vcc
	v_cmp_gt_i32_e32 vcc, 0, v45
	v_and_b32_e32 v33, 0xffffff80, v33
	v_sub_u32_e32 v33, v33, v83
	v_cndmask_b32_e32 v34, v34, v36, vcc
	v_and_b32_e32 v34, 0xffffff80, v34
	v_sub_u32_e32 v35, v34, v82
	v_add_u32_e32 v34, 0x7d, v33
	v_add_u32_e32 v33, 0x7e, v35
	v_not_b32_e32 v35, v47
	v_or_b32_e32 v36, 0x80000000, v47
	v_cmp_gt_i32_e32 vcc, 0, v47
	v_and_b32_e32 v32, 0xffffff80, v32
	v_bitop3_b32 v32, v32, s41, v68 bitop3:0x36
	v_cndmask_b32_e32 v35, v36, v35, vcc
	v_and_b32_e32 v35, 0xffffff80, v35
	v_sub_u32_e32 v35, v35, v82
	v_add_u32_e32 v35, 0x7c, v35
	ds_write_b128 v115, v[32:35]
	v_not_b32_e32 v32, v16
	v_or_b32_e32 v33, 0x80000000, v16
	v_cmp_gt_i32_e32 vcc, 0, v16
	v_xor_b32_e32 v34, -1, v18
	v_xor_b32_e32 v35, -1, v17
	v_cndmask_b32_e32 v16, v33, v32, vcc
	v_and_b32_e32 v33, 0x7fffffff, v18
	v_and_b32_e32 v32, 0x7fffffff, v17
	v_pk_add_f32 v[32:33], v[32:33], 0 neg_lo:[1,1] neg_hi:[1,1]
	v_cmp_gt_i32_e32 vcc, 0, v18
	v_and_b32_e32 v16, 0xffffff80, v16
	v_bitop3_b32 v16, v16, s25, v68 bitop3:0x36
	v_cndmask_b32_e32 v18, v33, v34, vcc
	v_cmp_gt_i32_e32 vcc, 0, v17
	v_or_b32_e32 v33, 0x80000000, v19
	v_and_b32_e32 v18, 0xffffff80, v18
	v_cndmask_b32_e32 v17, v32, v35, vcc
	v_not_b32_e32 v32, v19
	v_cmp_gt_i32_e32 vcc, 0, v19
	v_and_b32_e32 v17, 0xffffff80, v17
	v_sub_u32_e32 v17, v17, v68
	v_cndmask_b32_e32 v19, v33, v32, vcc
	v_and_b32_e32 v19, 0xffffff80, v19
	v_sub_u32_e32 v18, v18, v69
	v_sub_u32_e32 v19, v19, v68
	v_add_u32_e32 v18, 0x7d, v18
	v_add_u32_e32 v17, 0x7e, v17
	v_add_u32_e32 v19, 0x7c, v19
	ds_write_b128 v108, v[16:19] offset:16384
	v_not_b32_e32 v16, v20
	v_or_b32_e32 v17, 0x80000000, v20
	v_cmp_gt_i32_e32 vcc, 0, v20
	v_and_b32_e32 v19, 0x7fffffff, v22
	v_and_b32_e32 v18, 0x7fffffff, v21
	v_mfma_f32_32x32x16_bf16 v[0:15], v[164:167], v[194:197], v[0:15]
	v_cndmask_b32_e32 v16, v17, v16, vcc
	v_xor_b32_e32 v17, -1, v22
	v_add_f32_e64 v18, -v18, neg(0)
	v_add_f32_e64 v19, -v19, neg(0)
	v_cmp_gt_i32_e32 vcc, 0, v22
	v_xor_b32_e32 v20, -1, v21
	v_and_b32_e32 v16, 0xffffff80, v16
	v_cndmask_b32_e32 v17, v19, v17, vcc
	v_cmp_gt_i32_e32 vcc, 0, v21
	v_and_b32_e32 v17, 0xffffff80, v17
	v_sub_u32_e32 v17, v17, v71
	v_cndmask_b32_e32 v18, v18, v20, vcc
	v_and_b32_e32 v18, 0xffffff80, v18
	v_sub_u32_e32 v19, v18, v70
	v_add_u32_e32 v18, 0x7d, v17
	v_add_u32_e32 v17, 0x7e, v19
	v_not_b32_e32 v19, v23
	v_or_b32_e32 v20, 0x80000000, v23
	v_cmp_gt_i32_e32 vcc, 0, v23
	v_mfma_f32_32x32x16_bf16 v[0:15], v[186:189], v[198:201], v[0:15]
	v_bitop3_b32 v16, v16, s27, v68 bitop3:0x36
	v_cndmask_b32_e32 v19, v20, v19, vcc
	v_and_b32_e32 v19, 0xffffff80, v19
	v_sub_u32_e32 v19, v19, v70
	v_add_u32_e32 v19, 0x7c, v19
	ds_write_b128 v109, v[16:19] offset:16384
	v_not_b32_e32 v16, v24
	v_or_b32_e32 v17, 0x80000000, v24
	v_cmp_gt_i32_e32 vcc, 0, v24
	v_and_b32_e32 v19, 0x7fffffff, v26
	v_and_b32_e32 v18, 0x7fffffff, v25
	v_cndmask_b32_e32 v16, v17, v16, vcc
	v_xor_b32_e32 v17, -1, v26
	v_pk_add_f32 v[18:19], v[18:19], 0 neg_lo:[1,1] neg_hi:[1,1]
	v_cmp_gt_i32_e32 vcc, 0, v26
	v_xor_b32_e32 v20, -1, v25
	v_mfma_f32_32x32x16_bf16 v[0:15], v[224:227], v[216:219], v[0:15]
	v_cndmask_b32_e32 v17, v19, v17, vcc
	v_cmp_gt_i32_e32 vcc, 0, v25
	v_and_b32_e32 v17, 0xffffff80, v17
	v_sub_u32_e32 v17, v17, v73
	v_cndmask_b32_e32 v18, v18, v20, vcc
	v_and_b32_e32 v18, 0xffffff80, v18
	v_sub_u32_e32 v19, v18, v72
	v_add_u32_e32 v18, 0x7d, v17
	v_add_u32_e32 v17, 0x7e, v19
	v_not_b32_e32 v19, v27
	v_or_b32_e32 v20, 0x80000000, v27
	v_cmp_gt_i32_e32 vcc, 0, v27
	v_and_b32_e32 v16, 0xffffff80, v16
	v_bitop3_b32 v16, v16, s28, v68 bitop3:0x36
	v_cndmask_b32_e32 v19, v20, v19, vcc
	v_and_b32_e32 v19, 0xffffff80, v19
	v_sub_u32_e32 v19, v19, v72
	v_add_u32_e32 v19, 0x7c, v19
	ds_write_b128 v110, v[16:19] offset:16384
	v_not_b32_e32 v16, v28
	v_or_b32_e32 v17, 0x80000000, v28
	v_cmp_gt_i32_e32 vcc, 0, v28
	v_and_b32_e32 v19, 0x7fffffff, v30
	v_and_b32_e32 v18, 0x7fffffff, v29
	v_cndmask_b32_e32 v16, v17, v16, vcc
	v_xor_b32_e32 v17, -1, v30
	v_pk_add_f32 v[18:19], v[18:19], 0 neg_lo:[1,1] neg_hi:[1,1]
	v_cmp_gt_i32_e32 vcc, 0, v30
	v_xor_b32_e32 v20, -1, v29
	v_mfma_f32_32x32x16_bf16 v[0:15], v[228:231], v[220:223], v[0:15]
	v_cndmask_b32_e32 v17, v19, v17, vcc
	v_cmp_gt_i32_e32 vcc, 0, v29
	v_and_b32_e32 v17, 0xffffff80, v17
	v_sub_u32_e32 v17, v17, v75
	v_cndmask_b32_e32 v18, v18, v20, vcc
	v_and_b32_e32 v18, 0xffffff80, v18
	v_sub_u32_e32 v19, v18, v74
	v_add_u32_e32 v18, 0x7d, v17
	v_add_u32_e32 v17, 0x7e, v19
	v_not_b32_e32 v19, v31
	v_or_b32_e32 v20, 0x80000000, v31
	v_cmp_gt_i32_e32 vcc, 0, v31
	v_and_b32_e32 v16, 0xffffff80, v16
	v_bitop3_b32 v16, v16, s29, v68 bitop3:0x36
	v_cndmask_b32_e32 v19, v20, v19, vcc
	v_and_b32_e32 v19, 0xffffff80, v19
	v_sub_u32_e32 v19, v19, v74
	v_add_u32_e32 v19, 0x7c, v19
	ds_write_b128 v111, v[16:19] offset:16384
	v_not_b32_e32 v16, v0
	v_or_b32_e32 v17, 0x80000000, v0
	v_cmp_gt_i32_e32 vcc, 0, v0
	v_xor_b32_e32 v18, -1, v2
	v_xor_b32_e32 v19, -1, v1
	v_cndmask_b32_e32 v0, v17, v16, vcc
	v_and_b32_e32 v17, 0x7fffffff, v2
	v_and_b32_e32 v16, 0x7fffffff, v1
	v_pk_add_f32 v[16:17], v[16:17], 0 neg_lo:[1,1] neg_hi:[1,1]
	v_cmp_gt_i32_e32 vcc, 0, v2
	v_and_b32_e32 v0, 0xffffff80, v0
	v_bitop3_b32 v0, v0, s22, v68 bitop3:0x36
	v_cndmask_b32_e32 v2, v17, v18, vcc
	v_cmp_gt_i32_e32 vcc, 0, v1
	v_or_b32_e32 v17, 0x80000000, v3
	v_and_b32_e32 v2, 0xffffff80, v2
	v_cndmask_b32_e32 v1, v16, v19, vcc
	v_not_b32_e32 v16, v3
	v_cmp_gt_i32_e32 vcc, 0, v3
	v_and_b32_e32 v1, 0xffffff80, v1
	v_sub_u32_e32 v1, v1, v76
	v_cndmask_b32_e32 v3, v17, v16, vcc
	v_and_b32_e32 v3, 0xffffff80, v3
	v_sub_u32_e32 v2, v2, v77
	v_sub_u32_e32 v3, v3, v76
	v_add_u32_e32 v2, 0x7d, v2
	v_add_u32_e32 v1, 0x7e, v1
	v_add_u32_e32 v3, 0x7c, v3
	ds_write_b128 v112, v[0:3] offset:16384
	v_not_b32_e32 v0, v4
	v_or_b32_e32 v1, 0x80000000, v4
	v_cmp_gt_i32_e32 vcc, 0, v4
	v_and_b32_e32 v3, 0x7fffffff, v6
	v_and_b32_e32 v2, 0x7fffffff, v5
	v_cndmask_b32_e32 v0, v1, v0, vcc
	v_xor_b32_e32 v1, -1, v6
	v_pk_add_f32 v[2:3], v[2:3], 0 neg_lo:[1,1] neg_hi:[1,1]
	v_cmp_gt_i32_e32 vcc, 0, v6
	v_xor_b32_e32 v4, -1, v5
	v_and_b32_e32 v0, 0xffffff80, v0
	v_cndmask_b32_e32 v1, v3, v1, vcc
	v_cmp_gt_i32_e32 vcc, 0, v5
	v_and_b32_e32 v1, 0xffffff80, v1
	v_sub_u32_e32 v1, v1, v79
	v_cndmask_b32_e32 v2, v2, v4, vcc
	v_and_b32_e32 v2, 0xffffff80, v2
	v_sub_u32_e32 v3, v2, v78
	v_add_u32_e32 v2, 0x7d, v1
	v_add_u32_e32 v1, 0x7e, v3
	v_not_b32_e32 v3, v7
	v_or_b32_e32 v4, 0x80000000, v7
	v_cmp_gt_i32_e32 vcc, 0, v7
	v_bitop3_b32 v0, v0, s35, v68 bitop3:0x36
	s_nop 0
	v_cndmask_b32_e32 v3, v4, v3, vcc
	v_and_b32_e32 v3, 0xffffff80, v3
	v_sub_u32_e32 v3, v3, v78
	v_add_u32_e32 v3, 0x7c, v3
	ds_write_b128 v113, v[0:3] offset:16384
	v_not_b32_e32 v0, v8
	v_or_b32_e32 v1, 0x80000000, v8
	v_cmp_gt_i32_e32 vcc, 0, v8
	v_and_b32_e32 v3, 0x7fffffff, v10
	v_and_b32_e32 v2, 0x7fffffff, v9
	v_cndmask_b32_e32 v0, v1, v0, vcc
	v_xor_b32_e32 v1, -1, v10
	v_pk_add_f32 v[2:3], v[2:3], 0 neg_lo:[1,1] neg_hi:[1,1]
	v_cmp_gt_i32_e32 vcc, 0, v10
	v_xor_b32_e32 v4, -1, v9
	v_and_b32_e32 v0, 0xffffff80, v0
	v_cndmask_b32_e32 v1, v3, v1, vcc
	v_cmp_gt_i32_e32 vcc, 0, v9
	v_and_b32_e32 v1, 0xffffff80, v1
	v_sub_u32_e32 v1, v1, v81
	v_cndmask_b32_e32 v2, v2, v4, vcc
	v_and_b32_e32 v2, 0xffffff80, v2
	v_sub_u32_e32 v3, v2, v80
	v_add_u32_e32 v2, 0x7d, v1
	v_add_u32_e32 v1, 0x7e, v3
	v_not_b32_e32 v3, v11
	v_or_b32_e32 v4, 0x80000000, v11
	v_cmp_gt_i32_e32 vcc, 0, v11
	v_bitop3_b32 v0, v0, s40, v68 bitop3:0x36
	s_nop 0
	v_cndmask_b32_e32 v3, v4, v3, vcc
	v_and_b32_e32 v3, 0xffffff80, v3
	v_sub_u32_e32 v3, v3, v80
	v_add_u32_e32 v3, 0x7c, v3
	ds_write_b128 v114, v[0:3] offset:16384
	v_not_b32_e32 v0, v12
	v_or_b32_e32 v1, 0x80000000, v12
	v_cmp_gt_i32_e32 vcc, 0, v12
	v_and_b32_e32 v3, 0x7fffffff, v14
	v_and_b32_e32 v2, 0x7fffffff, v13
	v_cndmask_b32_e32 v0, v1, v0, vcc
	v_xor_b32_e32 v1, -1, v14
	v_pk_add_f32 v[2:3], v[2:3], 0 neg_lo:[1,1] neg_hi:[1,1]
	v_cmp_gt_i32_e32 vcc, 0, v14
	v_xor_b32_e32 v4, -1, v13
	v_and_b32_e32 v0, 0xffffff80, v0
	v_cndmask_b32_e32 v1, v3, v1, vcc
	v_cmp_gt_i32_e32 vcc, 0, v13
	v_and_b32_e32 v1, 0xffffff80, v1
	v_sub_u32_e32 v1, v1, v83
	v_cndmask_b32_e32 v2, v2, v4, vcc
	v_and_b32_e32 v2, 0xffffff80, v2
	v_sub_u32_e32 v3, v2, v82
	v_add_u32_e32 v2, 0x7d, v1
	v_add_u32_e32 v1, 0x7e, v3
	v_not_b32_e32 v3, v15
	v_or_b32_e32 v4, 0x80000000, v15
	v_cmp_gt_i32_e32 vcc, 0, v15
	v_bitop3_b32 v0, v0, s41, v68 bitop3:0x36
	s_nop 0
	v_cndmask_b32_e32 v3, v4, v3, vcc
	v_and_b32_e32 v3, 0xffffff80, v3
	v_sub_u32_e32 v3, v3, v82
	v_add_u32_e32 v3, 0x7c, v3
	ds_write_b128 v115, v[0:3] offset:16384
	s_waitcnt lgkmcnt(0)
	s_barrier
	ds_read_b128 v[0:3], v116
	ds_read_b128 v[4:7], v117
	ds_read_b128 v[8:11], v118
	ds_read_b128 v[12:15], v119
	ds_read_b128 v[16:19], v120
	ds_read_b128 v[20:23], v121
	ds_read_b128 v[24:27], v122
	ds_read_b128 v[28:31], v123
	ds_read_b128 v[32:35], v124
	ds_read_b128 v[36:39], v125
	ds_read_b128 v[40:43], v126
	ds_read_b128 v[44:47], v127
	ds_read_b128 v[48:51], v128
	ds_read_b128 v[52:55], v129
	ds_read_b128 v[56:59], v130
	ds_read_b128 v[60:63], v131
	s_waitcnt lgkmcnt(0)
	s_barrier
	v_max_u32_e32 v212, v0, v1
	v_min_u32_e32 v1, v0, v1
	v_max_u32_e32 v0, v16, v17
	v_min_u32_e32 v17, v16, v17
	v_max_u32_e32 v16, v32, v33
	v_min_u32_e32 v33, v32, v33
	v_max_u32_e32 v32, v48, v49
	v_min_u32_e32 v49, v48, v49
	v_max_u32_e32 v48, v2, v3
	v_min_u32_e32 v3, v2, v3
	v_max_u32_e32 v2, v18, v19
	v_min_u32_e32 v19, v18, v19
	v_max_u32_e32 v18, v34, v35
	v_min_u32_e32 v35, v34, v35
	v_max_u32_e32 v34, v50, v51
	v_min_u32_e32 v51, v50, v51
	v_max_u32_e32 v50, v212, v48
	v_min_u32_e32 v48, v212, v48
	v_max_u32_e32 v212, v0, v2
	v_min_u32_e32 v2, v0, v2
	v_max_u32_e32 v0, v16, v18
	v_min_u32_e32 v18, v16, v18
	v_max_u32_e32 v16, v32, v34
	v_min_u32_e32 v34, v32, v34
	v_max_u32_e32 v32, v1, v3
	v_min_u32_e32 v3, v1, v3
	v_max_u32_e32 v1, v17, v19
	v_min_u32_e32 v19, v17, v19
	v_max_u32_e32 v17, v33, v35
	v_min_u32_e32 v35, v33, v35
	v_max_u32_e32 v33, v49, v51
	v_min_u32_e32 v51, v49, v51
	v_max_u32_e32 v49, v32, v48
	v_min_u32_e32 v48, v32, v48
	v_max_u32_e32 v32, v1, v2
	v_min_u32_e32 v2, v1, v2
	v_max_u32_e32 v1, v17, v18
	v_min_u32_e32 v18, v17, v18
	v_max_u32_e32 v17, v33, v34
	v_min_u32_e32 v34, v33, v34
	v_max_u32_e32 v33, v4, v5
	v_min_u32_e32 v5, v4, v5
	v_max_u32_e32 v4, v20, v21
	v_min_u32_e32 v21, v20, v21
	v_max_u32_e32 v20, v36, v37
	v_min_u32_e32 v37, v36, v37
	v_max_u32_e32 v36, v52, v53
	v_min_u32_e32 v53, v52, v53
	v_max_u32_e32 v52, v6, v7
	v_min_u32_e32 v7, v6, v7
	v_max_u32_e32 v6, v22, v23
	v_min_u32_e32 v23, v22, v23
	v_max_u32_e32 v22, v38, v39
	v_min_u32_e32 v39, v38, v39
	v_max_u32_e32 v38, v54, v55
	v_min_u32_e32 v55, v54, v55
	v_max_u32_e32 v54, v33, v52
	v_min_u32_e32 v52, v33, v52
	v_max_u32_e32 v33, v4, v6
	v_min_u32_e32 v6, v4, v6
	v_max_u32_e32 v4, v20, v22
	v_min_u32_e32 v22, v20, v22
	v_max_u32_e32 v20, v36, v38
	v_min_u32_e32 v38, v36, v38
	v_max_u32_e32 v36, v5, v7
	v_min_u32_e32 v7, v5, v7
	v_max_u32_e32 v5, v21, v23
	v_min_u32_e32 v23, v21, v23
	v_max_u32_e32 v21, v37, v39
	v_min_u32_e32 v39, v37, v39
	v_max_u32_e32 v37, v53, v55
	v_min_u32_e32 v55, v53, v55
	v_max_u32_e32 v53, v36, v52
	v_min_u32_e32 v52, v36, v52
	v_max_u32_e32 v36, v5, v6
	v_min_u32_e32 v6, v5, v6
	v_max_u32_e32 v5, v21, v22
	v_min_u32_e32 v22, v21, v22
	v_max_u32_e32 v21, v37, v38
	v_min_u32_e32 v38, v37, v38
	v_max_u32_e32 v37, v50, v54
	v_min_u32_e32 v54, v50, v54
	v_max_u32_e32 v50, v212, v33
	v_min_u32_e32 v33, v212, v33
	v_max_u32_e32 v212, v0, v4
	v_min_u32_e32 v4, v0, v4
	v_max_u32_e32 v0, v16, v20
	v_min_u32_e32 v20, v16, v20
	v_max_u32_e32 v16, v48, v52
	v_min_u32_e32 v52, v48, v52
	v_max_u32_e32 v48, v2, v6
	v_min_u32_e32 v6, v2, v6
	v_max_u32_e32 v2, v18, v22
	v_min_u32_e32 v22, v18, v22
	v_max_u32_e32 v18, v34, v38
	v_min_u32_e32 v38, v34, v38
	v_max_u32_e32 v34, v16, v54
	v_min_u32_e32 v54, v16, v54
	v_max_u32_e32 v16, v48, v33
	v_min_u32_e32 v33, v48, v33
	v_max_u32_e32 v48, v2, v4
	v_min_u32_e32 v4, v2, v4
	v_max_u32_e32 v2, v18, v20
	v_min_u32_e32 v20, v18, v20
	v_max_u32_e32 v18, v49, v53
	v_min_u32_e32 v53, v49, v53
	v_max_u32_e32 v49, v32, v36
	v_min_u32_e32 v36, v32, v36
	v_max_u32_e32 v32, v1, v5
	v_min_u32_e32 v5, v1, v5
	v_max_u32_e32 v1, v17, v21
	v_min_u32_e32 v21, v17, v21
	v_max_u32_e32 v17, v3, v7
	v_min_u32_e32 v7, v3, v7
	v_max_u32_e32 v3, v19, v23
	v_min_u32_e32 v23, v19, v23
	v_max_u32_e32 v19, v35, v39
	v_min_u32_e32 v39, v35, v39
	v_max_u32_e32 v35, v51, v55
	v_min_u32_e32 v55, v51, v55
	v_max_u32_e32 v51, v17, v53
	v_min_u32_e32 v53, v17, v53
	v_max_u32_e32 v17, v3, v36
	v_min_u32_e32 v36, v3, v36
	v_max_u32_e32 v3, v19, v5
	v_min_u32_e32 v5, v19, v5
	v_max_u32_e32 v19, v35, v21
	v_min_u32_e32 v21, v35, v21
	v_max_u32_e32 v35, v18, v34
	v_min_u32_e32 v34, v18, v34
	v_max_u32_e32 v18, v49, v16
	v_min_u32_e32 v16, v49, v16
	v_max_u32_e32 v49, v32, v48
	v_min_u32_e32 v48, v32, v48
	v_max_u32_e32 v32, v1, v2
	v_min_u32_e32 v2, v1, v2
	v_max_u32_e32 v1, v51, v54
	v_min_u32_e32 v54, v51, v54
	v_max_u32_e32 v51, v17, v33
	v_min_u32_e32 v33, v17, v33
	v_max_u32_e32 v17, v3, v4
	v_min_u32_e32 v4, v3, v4
	v_max_u32_e32 v3, v19, v20
	v_min_u32_e32 v20, v19, v20
	v_max_u32_e32 v19, v53, v52
	v_min_u32_e32 v52, v53, v52
	v_max_u32_e32 v53, v36, v6
	v_min_u32_e32 v6, v36, v6
	v_max_u32_e32 v36, v5, v22
	v_min_u32_e32 v22, v5, v22
	v_max_u32_e32 v5, v21, v38
	v_min_u32_e32 v38, v21, v38
	v_max_u32_e32 v21, v8, v9
	v_min_u32_e32 v9, v8, v9
	v_max_u32_e32 v8, v24, v25
	v_min_u32_e32 v25, v24, v25
	v_max_u32_e32 v24, v40, v41
	v_min_u32_e32 v41, v40, v41
	v_max_u32_e32 v40, v56, v57
	v_min_u32_e32 v57, v56, v57
	v_max_u32_e32 v56, v10, v11
	v_min_u32_e32 v11, v10, v11
	v_max_u32_e32 v10, v26, v27
	v_min_u32_e32 v27, v26, v27
	v_max_u32_e32 v26, v42, v43
	v_min_u32_e32 v43, v42, v43
	v_max_u32_e32 v42, v58, v59
	v_min_u32_e32 v59, v58, v59
	v_max_u32_e32 v58, v21, v56
	v_min_u32_e32 v56, v21, v56
	v_max_u32_e32 v21, v8, v10
	v_min_u32_e32 v10, v8, v10
	v_max_u32_e32 v8, v24, v26
	v_min_u32_e32 v26, v24, v26
	v_max_u32_e32 v24, v40, v42
	v_min_u32_e32 v42, v40, v42
	v_max_u32_e32 v40, v9, v11
	v_min_u32_e32 v11, v9, v11
	v_max_u32_e32 v9, v25, v27
	v_min_u32_e32 v27, v25, v27
	v_max_u32_e32 v25, v41, v43
	v_min_u32_e32 v43, v41, v43
	v_max_u32_e32 v41, v57, v59
	v_min_u32_e32 v59, v57, v59
	v_max_u32_e32 v57, v40, v56
	v_min_u32_e32 v56, v40, v56
	v_max_u32_e32 v40, v9, v10
	v_min_u32_e32 v10, v9, v10
	v_max_u32_e32 v9, v25, v26
	v_min_u32_e32 v26, v25, v26
	v_max_u32_e32 v25, v41, v42
	v_min_u32_e32 v42, v41, v42
	v_max_u32_e32 v41, v12, v13
	v_min_u32_e32 v13, v12, v13
	v_max_u32_e32 v12, v28, v29
	v_min_u32_e32 v29, v28, v29
	v_max_u32_e32 v28, v44, v45
	v_min_u32_e32 v45, v44, v45
	v_max_u32_e32 v44, v60, v61
	v_min_u32_e32 v61, v60, v61
	v_max_u32_e32 v60, v14, v15
	v_min_u32_e32 v15, v14, v15
	v_max_u32_e32 v14, v30, v31
	v_min_u32_e32 v31, v30, v31
	v_max_u32_e32 v30, v46, v47
	v_min_u32_e32 v47, v46, v47
	v_max_u32_e32 v46, v62, v63
	v_min_u32_e32 v63, v62, v63
	v_max_u32_e32 v62, v41, v60
	v_min_u32_e32 v60, v41, v60
	v_max_u32_e32 v41, v12, v14
	v_min_u32_e32 v14, v12, v14
	v_max_u32_e32 v12, v28, v30
	v_min_u32_e32 v30, v28, v30
	v_max_u32_e32 v28, v44, v46
	v_min_u32_e32 v46, v44, v46
	v_max_u32_e32 v44, v13, v15
	v_min_u32_e32 v15, v13, v15
	v_max_u32_e32 v13, v29, v31
	v_min_u32_e32 v31, v29, v31
	v_max_u32_e32 v29, v45, v47
	v_min_u32_e32 v47, v45, v47
	v_max_u32_e32 v45, v61, v63
	v_min_u32_e32 v63, v61, v63
	v_max_u32_e32 v61, v44, v60
	v_min_u32_e32 v60, v44, v60
	v_max_u32_e32 v44, v13, v14
	v_min_u32_e32 v14, v13, v14
	v_max_u32_e32 v13, v29, v30
	v_min_u32_e32 v30, v29, v30
	v_max_u32_e32 v29, v45, v46
	v_min_u32_e32 v46, v45, v46
	v_max_u32_e32 v45, v58, v62
	v_min_u32_e32 v62, v58, v62
	v_max_u32_e32 v58, v21, v41
	v_min_u32_e32 v41, v21, v41
	v_max_u32_e32 v21, v8, v12
	v_min_u32_e32 v12, v8, v12
	v_max_u32_e32 v8, v24, v28
	v_min_u32_e32 v28, v24, v28
	v_max_u32_e32 v24, v56, v60
	v_min_u32_e32 v60, v56, v60
	v_max_u32_e32 v56, v10, v14
	v_min_u32_e32 v14, v10, v14
	v_max_u32_e32 v10, v26, v30
	v_min_u32_e32 v30, v26, v30
	v_max_u32_e32 v26, v42, v46
	v_min_u32_e32 v46, v42, v46
	v_max_u32_e32 v42, v24, v62
	v_min_u32_e32 v62, v24, v62
	v_max_u32_e32 v24, v56, v41
	v_min_u32_e32 v41, v56, v41
	v_max_u32_e32 v56, v10, v12
	v_min_u32_e32 v12, v10, v12
	v_max_u32_e32 v10, v26, v28
	v_min_u32_e32 v28, v26, v28
	v_max_u32_e32 v26, v57, v61
	v_min_u32_e32 v61, v57, v61
	v_max_u32_e32 v57, v40, v44
	v_min_u32_e32 v44, v40, v44
	v_max_u32_e32 v40, v9, v13
	v_min_u32_e32 v13, v9, v13
	v_max_u32_e32 v9, v25, v29
	v_min_u32_e32 v29, v25, v29
	v_max_u32_e32 v25, v11, v15
	v_min_u32_e32 v15, v11, v15
	v_max_u32_e32 v11, v27, v31
	v_min_u32_e32 v31, v27, v31
	v_max_u32_e32 v27, v43, v47
	v_min_u32_e32 v47, v43, v47
	v_max_u32_e32 v43, v59, v63
	v_min_u32_e32 v63, v59, v63
	v_max_u32_e32 v59, v25, v61
	v_min_u32_e32 v61, v25, v61
	v_max_u32_e32 v25, v11, v44
	v_min_u32_e32 v44, v11, v44
	v_max_u32_e32 v11, v27, v13
	v_min_u32_e32 v13, v27, v13
	v_max_u32_e32 v27, v43, v29
	v_min_u32_e32 v29, v43, v29
	v_max_u32_e32 v43, v26, v42
	v_min_u32_e32 v42, v26, v42
	v_max_u32_e32 v26, v57, v24
	v_min_u32_e32 v24, v57, v24
	v_max_u32_e32 v57, v40, v56
	v_min_u32_e32 v56, v40, v56
	v_max_u32_e32 v40, v9, v10
	v_min_u32_e32 v10, v9, v10
	v_max_u32_e32 v9, v59, v62
	v_min_u32_e32 v62, v59, v62
	v_max_u32_e32 v59, v25, v41
	v_min_u32_e32 v41, v25, v41
	v_max_u32_e32 v25, v11, v12
	v_min_u32_e32 v12, v11, v12
	v_max_u32_e32 v11, v27, v28
	v_min_u32_e32 v28, v27, v28
	v_max_u32_e32 v27, v61, v60
	v_min_u32_e32 v60, v61, v60
	v_max_u32_e32 v61, v44, v14
	v_min_u32_e32 v14, v44, v14
	v_max_u32_e32 v44, v13, v30
	v_min_u32_e32 v30, v13, v30
	v_max_u32_e32 v13, v29, v46
	v_min_u32_e32 v46, v29, v46
	v_max_u32_e32 v29, v37, v45
	v_min_u32_e32 v45, v37, v45
	v_max_u32_e32 v37, v50, v58
	v_min_u32_e32 v58, v50, v58
	v_max_u32_e32 v50, v212, v21
	v_min_u32_e32 v21, v212, v21
	v_max_u32_e32 v212, v0, v8
	v_min_u32_e32 v8, v0, v8
	v_max_u32_e32 v0, v54, v62
	v_min_u32_e32 v62, v54, v62
	v_max_u32_e32 v54, v33, v41
	v_min_u32_e32 v41, v33, v41
	v_max_u32_e32 v33, v4, v12
	v_min_u32_e32 v12, v4, v12
	v_max_u32_e32 v4, v20, v28
	v_min_u32_e32 v28, v20, v28
	v_max_u32_e32 v20, v0, v45
	v_min_u32_e32 v45, v0, v45
	v_max_u32_e32 v0, v54, v58
	v_min_u32_e32 v58, v54, v58
	v_max_u32_e32 v54, v33, v21
	v_min_u32_e32 v21, v33, v21
	v_max_u32_e32 v33, v4, v8
	v_min_u32_e32 v8, v4, v8
	v_max_u32_e32 v4, v34, v42
	v_min_u32_e32 v42, v34, v42
	v_max_u32_e32 v34, v16, v24
	v_min_u32_e32 v24, v16, v24
	v_max_u32_e32 v16, v48, v56
	v_min_u32_e32 v56, v48, v56
	v_max_u32_e32 v48, v2, v10
	v_min_u32_e32 v10, v2, v10
	v_max_u32_e32 v2, v52, v60
	v_min_u32_e32 v60, v52, v60
	v_max_u32_e32 v52, v6, v14
	v_min_u32_e32 v14, v6, v14
	v_max_u32_e32 v6, v22, v30
	v_min_u32_e32 v30, v22, v30
	v_max_u32_e32 v22, v38, v46
	v_min_u32_e32 v46, v38, v46
	v_max_u32_e32 v38, v2, v42
	v_min_u32_e32 v42, v2, v42
	v_max_u32_e32 v2, v52, v24
	v_min_u32_e32 v24, v52, v24
	v_max_u32_e32 v52, v6, v56
	v_min_u32_e32 v56, v6, v56
	v_max_u32_e32 v6, v22, v10
	v_min_u32_e32 v10, v22, v10
	v_max_u32_e32 v22, v4, v20
	v_min_u32_e32 v20, v4, v20
	v_max_u32_e32 v4, v34, v0
	v_min_u32_e32 v0, v34, v0
	v_max_u32_e32 v34, v16, v54
	v_min_u32_e32 v54, v16, v54
	v_max_u32_e32 v16, v48, v33
	v_min_u32_e32 v33, v48, v33
	v_max_u32_e32 v48, v38, v45
	v_min_u32_e32 v45, v38, v45
	v_max_u32_e32 v38, v2, v58
	v_min_u32_e32 v58, v2, v58
	v_max_u32_e32 v2, v52, v21
	v_min_u32_e32 v21, v52, v21
	v_max_u32_e32 v52, v6, v8
	v_min_u32_e32 v8, v6, v8
	v_max_u32_e32 v6, v42, v62
	v_min_u32_e32 v62, v42, v62
	v_max_u32_e32 v42, v24, v41
	v_min_u32_e32 v41, v24, v41
	v_max_u32_e32 v24, v56, v12
	v_min_u32_e32 v12, v56, v12
	v_max_u32_e32 v56, v10, v28
	v_min_u32_e32 v28, v10, v28
	v_max_u32_e32 v10, v35, v43
	v_min_u32_e32 v43, v35, v43
	v_max_u32_e32 v35, v18, v26
	v_min_u32_e32 v26, v18, v26
	v_max_u32_e32 v18, v49, v57
	v_min_u32_e32 v57, v49, v57
	v_max_u32_e32 v49, v32, v40
	v_min_u32_e32 v40, v32, v40
	v_max_u32_e32 v32, v19, v27
	v_min_u32_e32 v27, v19, v27
	v_max_u32_e32 v19, v53, v61
	v_min_u32_e32 v61, v53, v61
	v_max_u32_e32 v53, v36, v44
	v_min_u32_e32 v44, v36, v44
	v_max_u32_e32 v36, v5, v13
	v_min_u32_e32 v13, v5, v13
	v_max_u32_e32 v5, v32, v43
	v_min_u32_e32 v43, v32, v43
	v_max_u32_e32 v32, v19, v26
	v_min_u32_e32 v26, v19, v26
	v_max_u32_e32 v19, v53, v57
	v_min_u32_e32 v57, v53, v57
	v_max_u32_e32 v53, v36, v40
	v_min_u32_e32 v40, v36, v40
	v_max_u32_e32 v36, v1, v9
	v_min_u32_e32 v9, v1, v9
	v_max_u32_e32 v1, v51, v59
	v_min_u32_e32 v59, v51, v59
	v_max_u32_e32 v51, v17, v25
	v_min_u32_e32 v25, v17, v25
	v_max_u32_e32 v17, v3, v11
	v_min_u32_e32 v11, v3, v11
	v_max_u32_e32 v3, v7, v15
	v_min_u32_e32 v15, v7, v15
	v_max_u32_e32 v7, v23, v31
	v_min_u32_e32 v31, v23, v31
	v_max_u32_e32 v23, v39, v47
	v_min_u32_e32 v47, v39, v47
	v_max_u32_e32 v39, v55, v63
	v_min_u32_e32 v63, v55, v63
	v_max_u32_e32 v55, v3, v9
	v_min_u32_e32 v9, v3, v9
	v_max_u32_e32 v3, v7, v59
	v_min_u32_e32 v59, v7, v59
	v_max_u32_e32 v7, v23, v25
	v_min_u32_e32 v25, v23, v25
	v_max_u32_e32 v23, v39, v11
	v_min_u32_e32 v11, v39, v11
	v_max_u32_e32 v39, v36, v5
	v_min_u32_e32 v5, v36, v5
	v_max_u32_e32 v36, v1, v32
	v_min_u32_e32 v32, v1, v32
	v_max_u32_e32 v1, v51, v19
	v_min_u32_e32 v19, v51, v19
	v_max_u32_e32 v51, v17, v53
	v_min_u32_e32 v53, v17, v53
	v_max_u32_e32 v17, v55, v43
	v_min_u32_e32 v43, v55, v43
	v_max_u32_e32 v55, v3, v26
	v_min_u32_e32 v26, v3, v26
	v_max_u32_e32 v3, v7, v57
	v_min_u32_e32 v57, v7, v57
	v_max_u32_e32 v7, v23, v40
	v_min_u32_e32 v40, v23, v40
	v_max_u32_e32 v23, v9, v27
	v_min_u32_e32 v27, v9, v27
	v_max_u32_e32 v9, v59, v61
	v_min_u32_e32 v61, v59, v61
	v_max_u32_e32 v59, v25, v44
	v_min_u32_e32 v44, v25, v44
	v_max_u32_e32 v25, v11, v13
	v_min_u32_e32 v13, v11, v13
	v_max_u32_e32 v11, v10, v22
	v_min_u32_e32 v22, v10, v22
	v_max_u32_e32 v10, v35, v4
	v_min_u32_e32 v4, v35, v4
	v_max_u32_e32 v35, v18, v34
	v_min_u32_e32 v34, v18, v34
	v_max_u32_e32 v18, v49, v16
	v_min_u32_e32 v16, v49, v16
	v_max_u32_e32 v49, v39, v20
	v_min_u32_e32 v20, v39, v20
	v_max_u32_e32 v39, v36, v0
	v_min_u32_e32 v0, v36, v0
	v_max_u32_e32 v36, v1, v54
	v_min_u32_e32 v54, v1, v54
	v_max_u32_e32 v1, v51, v33
	v_min_u32_e32 v33, v51, v33
	v_max_u32_e32 v51, v5, v48
	v_min_u32_e32 v48, v5, v48
	v_max_u32_e32 v5, v32, v38
	v_min_u32_e32 v38, v32, v38
	v_max_u32_e32 v32, v19, v2
	v_min_u32_e32 v2, v19, v2
	v_max_u32_e32 v19, v53, v52
	v_min_u32_e32 v52, v53, v52
	v_max_u32_e32 v53, v17, v45
	v_min_u32_e32 v45, v17, v45
	v_max_u32_e32 v17, v55, v58
	v_min_u32_e32 v58, v55, v58
	v_max_u32_e32 v55, v3, v21
	v_min_u32_e32 v21, v3, v21
	v_max_u32_e32 v3, v7, v8
	v_min_u32_e32 v8, v7, v8
	v_max_u32_e32 v7, v43, v6
	v_min_u32_e32 v6, v43, v6
	v_max_u32_e32 v43, v26, v42
	v_min_u32_e32 v42, v26, v42
	v_max_u32_e32 v26, v57, v24
	v_min_u32_e32 v24, v57, v24
	v_max_u32_e32 v57, v40, v56
	v_min_u32_e32 v56, v40, v56
	v_max_u32_e32 v40, v23, v62
	v_min_u32_e32 v62, v23, v62
	v_max_u32_e32 v23, v9, v41
	v_min_u32_e32 v41, v9, v41
	v_max_u32_e32 v9, v59, v12
	v_min_u32_e32 v12, v59, v12
	v_max_u32_e32 v59, v25, v28
	v_min_u32_e32 v28, v25, v28
	v_max_u32_e32 v25, v27, v60
	v_min_u32_e32 v60, v27, v60
	v_max_u32_e32 v27, v61, v14
	v_min_u32_e32 v14, v61, v14
	v_max_u32_e32 v61, v44, v30
	v_min_u32_e32 v30, v44, v30
	v_max_u32_e32 v44, v13, v46
	v_min_u32_e32 v46, v13, v46
	v_max_u32_e32 v29, v29, v31
	v_max_u32_e32 v11, v11, v14
	v_max_u32_e32 v22, v22, v27
	v_max_u32_e32 v49, v49, v41
	v_max_u32_e32 v20, v20, v23
	v_max_u32_e32 v51, v51, v42
	v_max_u32_e32 v48, v48, v43
	v_max_u32_e32 v53, v53, v58
	v_max_u32_e32 v45, v45, v17
	v_max_u32_e32 v7, v7, v38
	v_max_u32_e32 v6, v6, v5
	v_max_u32_e32 v40, v40, v0
	v_max_u32_e32 v62, v62, v39
	v_max_u32_e32 v25, v25, v4
	v_max_u32_e32 v60, v60, v10
	v_max_u32_e32 v15, v15, v37
	v_max_u32_e32 v13, v29, v45
	v_min_u32_e32 v45, v29, v45
	v_max_u32_e32 v29, v11, v7
	v_min_u32_e32 v7, v11, v7
	v_max_u32_e32 v11, v22, v6
	v_min_u32_e32 v6, v22, v6
	v_max_u32_e32 v22, v49, v40
	v_min_u32_e32 v40, v49, v40
	v_max_u32_e32 v49, v20, v62
	v_min_u32_e32 v62, v20, v62
	v_max_u32_e32 v20, v51, v25
	v_min_u32_e32 v25, v51, v25
	v_max_u32_e32 v51, v48, v60
	v_min_u32_e32 v60, v48, v60
	v_max_u32_e32 v48, v53, v15
	v_min_u32_e32 v15, v53, v15
	v_max_u32_e32 v53, v13, v49
	v_min_u32_e32 v49, v13, v49
	v_max_u32_e32 v13, v29, v20
	v_min_u32_e32 v20, v29, v20
	v_max_u32_e32 v29, v11, v51
	v_min_u32_e32 v51, v11, v51
	v_max_u32_e32 v11, v22, v48
	v_min_u32_e32 v48, v22, v48
	v_max_u32_e32 v22, v45, v62
	v_min_u32_e32 v62, v45, v62
	v_max_u32_e32 v45, v7, v25
	v_min_u32_e32 v25, v7, v25
	v_max_u32_e32 v7, v6, v60
	v_min_u32_e32 v60, v6, v60
	v_max_u32_e32 v6, v40, v15
	v_min_u32_e32 v15, v40, v15
	v_max_u32_e32 v40, v53, v29
	v_min_u32_e32 v29, v53, v29
	v_max_u32_e32 v53, v13, v11
	v_min_u32_e32 v11, v13, v11
	v_max_u32_e32 v13, v49, v51
	v_min_u32_e32 v51, v49, v51
	v_max_u32_e32 v49, v20, v48
	v_min_u32_e32 v48, v20, v48
	v_max_u32_e32 v20, v22, v7
	v_min_u32_e32 v7, v22, v7
	v_max_u32_e32 v22, v45, v6
	v_min_u32_e32 v6, v45, v6
	v_max_u32_e32 v45, v62, v60
	v_min_u32_e32 v60, v62, v60
	v_max_u32_e32 v62, v25, v15
	v_min_u32_e32 v15, v25, v15
	v_max_u32_e32 v25, v40, v53
	v_min_u32_e32 v53, v40, v53
	v_max_u32_e32 v40, v29, v11
	v_min_u32_e32 v11, v29, v11
	v_max_u32_e32 v29, v13, v49
	v_min_u32_e32 v49, v13, v49
	v_max_u32_e32 v13, v51, v48
	v_min_u32_e32 v48, v51, v48
	v_max_u32_e32 v51, v20, v22
	v_min_u32_e32 v22, v20, v22
	v_max_u32_e32 v20, v7, v6
	v_min_u32_e32 v6, v7, v6
	v_max_u32_e32 v7, v45, v62
	v_min_u32_e32 v62, v45, v62
	v_max_u32_e32 v45, v60, v15
	v_min_u32_e32 v15, v60, v15
	v_max_u32_e32 v50, v50, v63
	v_max_u32_e32 v35, v35, v46
	v_max_u32_e32 v34, v34, v44
	v_max_u32_e32 v36, v36, v28
	v_max_u32_e32 v54, v54, v59
	v_max_u32_e32 v32, v32, v56
	v_max_u32_e32 v2, v2, v57
	v_max_u32_e32 v55, v55, v8
	v_max_u32_e32 v21, v21, v3
	v_max_u32_e32 v26, v26, v52
	v_max_u32_e32 v24, v24, v19
	v_max_u32_e32 v9, v9, v33
	v_max_u32_e32 v12, v12, v1
	v_max_u32_e32 v61, v61, v16
	v_max_u32_e32 v30, v30, v18
	v_max_u32_e32 v47, v47, v212
	v_max_u32_e32 v60, v50, v21
	v_min_u32_e32 v21, v50, v21
	v_max_u32_e32 v50, v35, v26
	v_min_u32_e32 v26, v35, v26
	v_max_u32_e32 v35, v34, v24
	v_min_u32_e32 v24, v34, v24
	v_max_u32_e32 v34, v36, v9
	v_min_u32_e32 v9, v36, v9
	v_max_u32_e32 v36, v54, v12
	v_min_u32_e32 v12, v54, v12
	v_max_u32_e32 v54, v32, v61
	v_min_u32_e32 v61, v32, v61
	v_max_u32_e32 v32, v2, v30
	v_min_u32_e32 v30, v2, v30
	v_max_u32_e32 v2, v55, v47
	v_min_u32_e32 v47, v55, v47
	v_max_u32_e32 v55, v60, v36
	v_min_u32_e32 v36, v60, v36
	v_max_u32_e32 v60, v50, v54
	v_min_u32_e32 v54, v50, v54
	v_max_u32_e32 v50, v35, v32
	v_min_u32_e32 v32, v35, v32
	v_max_u32_e32 v35, v34, v2
	v_min_u32_e32 v2, v34, v2
	v_max_u32_e32 v34, v21, v12
	v_min_u32_e32 v12, v21, v12
	v_max_u32_e32 v21, v26, v61
	v_min_u32_e32 v61, v26, v61
	v_max_u32_e32 v26, v24, v30
	v_min_u32_e32 v30, v24, v30
	v_max_u32_e32 v24, v9, v47
	v_min_u32_e32 v47, v9, v47
	v_max_u32_e32 v9, v55, v50
	v_min_u32_e32 v50, v55, v50
	v_max_u32_e32 v55, v60, v35
	v_min_u32_e32 v35, v60, v35
	v_max_u32_e32 v60, v36, v32
	v_min_u32_e32 v32, v36, v32
	v_max_u32_e32 v36, v54, v2
	v_min_u32_e32 v2, v54, v2
	v_max_u32_e32 v54, v34, v26
	v_min_u32_e32 v26, v34, v26
	v_max_u32_e32 v34, v21, v24
	v_min_u32_e32 v24, v21, v24
	v_max_u32_e32 v21, v12, v30
	v_min_u32_e32 v30, v12, v30
	v_max_u32_e32 v12, v61, v47
	v_min_u32_e32 v47, v61, v47
	v_max_u32_e32 v61, v9, v55
	v_min_u32_e32 v55, v9, v55
	v_max_u32_e32 v9, v50, v35
	v_min_u32_e32 v35, v50, v35
	v_max_u32_e32 v50, v60, v36
	v_min_u32_e32 v36, v60, v36
	v_max_u32_e32 v60, v32, v2
	v_min_u32_e32 v2, v32, v2
	v_max_u32_e32 v32, v54, v34
	v_min_u32_e32 v34, v54, v34
	v_max_u32_e32 v54, v26, v24
	v_min_u32_e32 v24, v26, v24
	v_max_u32_e32 v26, v21, v12
	v_min_u32_e32 v12, v21, v12
	v_max_u32_e32 v21, v30, v47
	v_min_u32_e32 v47, v30, v47
	v_max_u32_e32 v25, v25, v47
	v_max_u32_e32 v53, v53, v21
	v_max_u32_e32 v40, v40, v12
	v_max_u32_e32 v11, v11, v26
	v_max_u32_e32 v29, v29, v24
	v_max_u32_e32 v49, v49, v54
	v_max_u32_e32 v13, v13, v34
	v_max_u32_e32 v48, v48, v32
	v_max_u32_e32 v51, v51, v2
	v_max_u32_e32 v22, v22, v60
	v_max_u32_e32 v20, v20, v36
	v_max_u32_e32 v6, v6, v50
	v_max_u32_e32 v7, v7, v35
	v_max_u32_e32 v62, v62, v9
	v_max_u32_e32 v45, v45, v55
	v_max_u32_e32 v15, v15, v61
	v_max_u32_e32 v30, v25, v51
	v_min_u32_e32 v51, v25, v51
	v_max_u32_e32 v25, v53, v22
	v_min_u32_e32 v22, v53, v22
	v_max_u32_e32 v53, v40, v20
	v_min_u32_e32 v20, v40, v20
	v_max_u32_e32 v40, v11, v6
	v_min_u32_e32 v6, v11, v6
	v_max_u32_e32 v11, v29, v7
	v_min_u32_e32 v7, v29, v7
	v_max_u32_e32 v29, v49, v62
	v_min_u32_e32 v62, v49, v62
	v_max_u32_e32 v49, v13, v45
	v_min_u32_e32 v45, v13, v45
	v_max_u32_e32 v13, v48, v15
	v_min_u32_e32 v15, v48, v15
	v_max_u32_e32 v48, v30, v11
	v_min_u32_e32 v11, v30, v11
	v_max_u32_e32 v30, v25, v29
	v_min_u32_e32 v29, v25, v29
	v_max_u32_e32 v25, v53, v49
	v_min_u32_e32 v49, v53, v49
	v_max_u32_e32 v53, v40, v13
	v_min_u32_e32 v13, v40, v13
	v_max_u32_e32 v40, v51, v7
	v_min_u32_e32 v7, v51, v7
	v_max_u32_e32 v51, v22, v62
	v_min_u32_e32 v62, v22, v62
	v_max_u32_e32 v22, v20, v45
	v_min_u32_e32 v45, v20, v45
	v_max_u32_e32 v20, v6, v15
	v_min_u32_e32 v15, v6, v15
	v_max_u32_e32 v6, v48, v25
	v_min_u32_e32 v25, v48, v25
	v_max_u32_e32 v48, v30, v53
	v_min_u32_e32 v53, v30, v53
	v_max_u32_e32 v30, v11, v49
	v_min_u32_e32 v49, v11, v49
	v_max_u32_e32 v11, v29, v13
	v_min_u32_e32 v13, v29, v13
	v_max_u32_e32 v29, v40, v22
	v_min_u32_e32 v22, v40, v22
	v_max_u32_e32 v40, v51, v20
	v_min_u32_e32 v20, v51, v20
	v_max_u32_e32 v51, v7, v45
	v_min_u32_e32 v45, v7, v45
	v_max_u32_e32 v7, v62, v15
	v_min_u32_e32 v15, v62, v15
	v_max_u32_e32 v62, v6, v48
	v_min_u32_e32 v48, v6, v48
	v_max_u32_e32 v6, v25, v53
	v_min_u32_e32 v53, v25, v53
	v_max_u32_e32 v25, v30, v11
	v_min_u32_e32 v11, v30, v11
	v_max_u32_e32 v30, v49, v13
	v_min_u32_e32 v13, v49, v13
	v_max_u32_e32 v49, v29, v40
	v_min_u32_e32 v40, v29, v40
	v_max_u32_e32 v29, v22, v20
	v_min_u32_e32 v20, v22, v20
	v_max_u32_e32 v22, v51, v7
	v_min_u32_e32 v7, v51, v7
	v_max_u32_e32 v51, v45, v15
	v_min_u32_e32 v15, v45, v15
	v_cmp_gt_i32_e32 vcc, 0, v62
	v_and_b32_e32 v213, 0x7fffff80, v62
	v_not_b32_e32 v214, v62
	v_or_b32_e32 v214, 0x7f, v214
	v_cndmask_b32_e32 v213, v214, v213, vcc
	v_not_b32_e32 v215, v62
	v_and_b32_e32 v215, 0x7f, v215
	ds_write_b32 v106, v213
	ds_write_b32 v106, v215 offset:16384
	v_cmp_gt_i32_e32 vcc, 0, v48
	v_and_b32_e32 v214, 0x7fffff80, v48
	v_not_b32_e32 v215, v48
	v_or_b32_e32 v215, 0x7f, v215
	v_cndmask_b32_e32 v214, v215, v214, vcc
	v_not_b32_e32 v213, v48
	v_and_b32_e32 v213, 0x7f, v213
	ds_write_b32 v106, v214 offset:1024
	ds_write_b32 v106, v213 offset:17408
	v_cmp_gt_i32_e32 vcc, 0, v6
	v_and_b32_e32 v215, 0x7fffff80, v6
	v_not_b32_e32 v213, v6
	v_or_b32_e32 v213, 0x7f, v213
	v_cndmask_b32_e32 v215, v213, v215, vcc
	v_not_b32_e32 v214, v6
	v_and_b32_e32 v214, 0x7f, v214
	ds_write_b32 v106, v215 offset:2048
	ds_write_b32 v106, v214 offset:18432
	v_cmp_gt_i32_e32 vcc, 0, v53
	v_and_b32_e32 v213, 0x7fffff80, v53
	v_not_b32_e32 v214, v53
	v_or_b32_e32 v214, 0x7f, v214
	v_cndmask_b32_e32 v213, v214, v213, vcc
	v_not_b32_e32 v215, v53
	v_and_b32_e32 v215, 0x7f, v215
	ds_write_b32 v106, v213 offset:3072
	ds_write_b32 v106, v215 offset:19456
	v_cmp_gt_i32_e32 vcc, 0, v25
	v_and_b32_e32 v214, 0x7fffff80, v25
	v_not_b32_e32 v215, v25
	v_or_b32_e32 v215, 0x7f, v215
	v_cndmask_b32_e32 v214, v215, v214, vcc
	v_not_b32_e32 v213, v25
	v_and_b32_e32 v213, 0x7f, v213
	ds_write_b32 v106, v214 offset:4096
	ds_write_b32 v106, v213 offset:20480
	v_cmp_gt_i32_e32 vcc, 0, v11
	v_and_b32_e32 v215, 0x7fffff80, v11
	v_not_b32_e32 v213, v11
	v_or_b32_e32 v213, 0x7f, v213
	v_cndmask_b32_e32 v215, v213, v215, vcc
	v_not_b32_e32 v214, v11
	v_and_b32_e32 v214, 0x7f, v214
	ds_write_b32 v106, v215 offset:5120
	ds_write_b32 v106, v214 offset:21504
	v_cmp_gt_i32_e32 vcc, 0, v30
	v_and_b32_e32 v213, 0x7fffff80, v30
	v_not_b32_e32 v214, v30
	v_or_b32_e32 v214, 0x7f, v214
	v_cndmask_b32_e32 v213, v214, v213, vcc
	v_not_b32_e32 v215, v30
	v_and_b32_e32 v215, 0x7f, v215
	ds_write_b32 v106, v213 offset:6144
	ds_write_b32 v106, v215 offset:22528
	v_cmp_gt_i32_e32 vcc, 0, v13
	v_and_b32_e32 v214, 0x7fffff80, v13
	v_not_b32_e32 v215, v13
	v_or_b32_e32 v215, 0x7f, v215
	v_cndmask_b32_e32 v214, v215, v214, vcc
	v_not_b32_e32 v213, v13
	v_and_b32_e32 v213, 0x7f, v213
	ds_write_b32 v106, v214 offset:7168
	ds_write_b32 v106, v213 offset:23552
	v_cmp_gt_i32_e32 vcc, 0, v49
	v_and_b32_e32 v215, 0x7fffff80, v49
	v_not_b32_e32 v213, v49
	v_or_b32_e32 v213, 0x7f, v213
	v_cndmask_b32_e32 v215, v213, v215, vcc
	v_not_b32_e32 v214, v49
	v_and_b32_e32 v214, 0x7f, v214
	ds_write_b32 v106, v215 offset:8192
	ds_write_b32 v106, v214 offset:24576
	v_cmp_gt_i32_e32 vcc, 0, v40
	v_and_b32_e32 v213, 0x7fffff80, v40
	v_not_b32_e32 v214, v40
	v_or_b32_e32 v214, 0x7f, v214
	v_cndmask_b32_e32 v213, v214, v213, vcc
	v_not_b32_e32 v215, v40
	v_and_b32_e32 v215, 0x7f, v215
	ds_write_b32 v106, v213 offset:9216
	ds_write_b32 v106, v215 offset:25600
	v_cmp_gt_i32_e32 vcc, 0, v29
	v_and_b32_e32 v214, 0x7fffff80, v29
	v_not_b32_e32 v215, v29
	v_or_b32_e32 v215, 0x7f, v215
	v_cndmask_b32_e32 v214, v215, v214, vcc
	v_not_b32_e32 v213, v29
	v_and_b32_e32 v213, 0x7f, v213
	ds_write_b32 v106, v214 offset:10240
	ds_write_b32 v106, v213 offset:26624
	v_cmp_gt_i32_e32 vcc, 0, v20
	v_and_b32_e32 v215, 0x7fffff80, v20
	v_not_b32_e32 v213, v20
	v_or_b32_e32 v213, 0x7f, v213
	v_cndmask_b32_e32 v215, v213, v215, vcc
	v_not_b32_e32 v214, v20
	v_and_b32_e32 v214, 0x7f, v214
	ds_write_b32 v106, v215 offset:11264
	ds_write_b32 v106, v214 offset:27648
	v_cmp_gt_i32_e32 vcc, 0, v22
	v_and_b32_e32 v213, 0x7fffff80, v22
	v_not_b32_e32 v214, v22
	v_or_b32_e32 v214, 0x7f, v214
	v_cndmask_b32_e32 v213, v214, v213, vcc
	v_not_b32_e32 v215, v22
	v_and_b32_e32 v215, 0x7f, v215
	ds_write_b32 v106, v213 offset:12288
	ds_write_b32 v106, v215 offset:28672
	v_cmp_gt_i32_e32 vcc, 0, v7
	v_and_b32_e32 v214, 0x7fffff80, v7
	v_not_b32_e32 v215, v7
	v_or_b32_e32 v215, 0x7f, v215
	v_cndmask_b32_e32 v214, v215, v214, vcc
	v_not_b32_e32 v213, v7
	v_and_b32_e32 v213, 0x7f, v213
	ds_write_b32 v106, v214 offset:13312
	ds_write_b32 v106, v213 offset:29696
	v_cmp_gt_i32_e32 vcc, 0, v51
	v_and_b32_e32 v215, 0x7fffff80, v51
	v_not_b32_e32 v213, v51
	v_or_b32_e32 v213, 0x7f, v213
	v_cndmask_b32_e32 v215, v213, v215, vcc
	v_not_b32_e32 v214, v51
	v_and_b32_e32 v214, 0x7f, v214
	ds_write_b32 v106, v215 offset:14336
	ds_write_b32 v106, v214 offset:30720
	v_cmp_gt_i32_e32 vcc, 0, v15
	v_and_b32_e32 v213, 0x7fffff80, v15
	v_not_b32_e32 v214, v15
	v_or_b32_e32 v214, 0x7f, v214
	v_cndmask_b32_e32 v213, v214, v213, vcc
	v_not_b32_e32 v215, v15
	v_and_b32_e32 v215, 0x7f, v215
	ds_write_b32 v106, v213 offset:15360
	ds_write_b32 v106, v215 offset:31744
	s_waitcnt lgkmcnt(0)
	s_barrier
	s_and_saveexec_b64 s[20:21], s[6:7]
	s_cbranch_execz .LBB0_1083
	s_and_b64 s[8:9], s[18:19], exec
	s_cselect_b32 s0, s23, s42
	s_cselect_b32 s8, s24, s43
	v_add_u32_e32 v0, s8, v156
	v_add_u32_e32 v1, s0, v162
	s_mov_b32 s0, 0
	v_mov_b32_e32 v2, 0
	v_mov_b32_e32 v3, 0
